# v15 + snake MFMA order inside each 16-MFMA block: every MFMA shares srcA or srcB tuple with its predecessor
# speedup vs baseline: 1.0055x; 1.0055x over previous
.LBB0_364:
	s_add_u32 s20, s18, 0xfff80080
	s_addc_u32 s21, s19, -1
	s_add_i32 s30, 0, 0x10000
	s_cmp_eq_u32 s29, 28
	s_cselect_b32 s23, s4, s21
	s_cselect_b32 s22, s24, s20
	s_cselect_b32 s21, s25, s28
	s_cselect_b32 s20, s26, s27
	s_add_i32 s42, 0, 0x14000
	v_add_u32_e32 v142, s30, v204
	v_add_u32_e32 v166, s42, v204
	ds_read_b128 v[130:133], v142
	ds_read_b128 v[134:137], v142 offset:1024
	ds_read_b128 v[138:141], v142 offset:2048
	ds_read_b128 v[142:145], v142 offset:3072
	ds_read_b128 v[146:149], v166
	ds_read_b128 v[150:153], v166 offset:1024
	ds_read_b128 v[154:157], v166 offset:2048
	ds_read_b128 v[166:169], v166 offset:3072
	v_lshl_add_u64 v[202:203], s[18:19], 0, v[162:163]
	s_add_i32 m0, s87, 0xc000
	ds_read_b128 v[170:173], v205
	ds_read_b128 v[174:177], v205 offset:1024
	ds_read_b128 v[178:181], v205 offset:2048
	ds_read_b128 v[182:185], v205 offset:3072
	ds_read_b128 v[186:189], v205 offset:4096
	ds_read_b128 v[190:193], v205 offset:5120
	ds_read_b128 v[206:209], v205 offset:6144
	ds_read_b128 v[210:213], v205 offset:7168
	global_load_lds_dwordx4 v[202:203], off
	v_lshl_add_u64 v[202:203], s[18:19], 0, v[164:165]
	s_add_i32 m0, s87, 0xe000
	s_nop 0
	global_load_lds_dwordx4 v[202:203], off
	s_waitcnt vmcnt(8)
	s_waitcnt lgkmcnt(0)
	s_setprio 1
	s_barrier
	v_mfma_f32_16x16x32_bf16 v[126:129], v[130:133], v[170:173], v[126:129]
	v_mfma_f32_16x16x32_bf16 v[122:125], v[138:141], v[170:173], v[122:125]
	v_mfma_f32_16x16x32_bf16 v[106:109], v[138:141], v[178:181], v[106:109]
	v_mfma_f32_16x16x32_bf16 v[110:113], v[130:133], v[178:181], v[110:113]
	v_mfma_f32_16x16x32_bf16 v[94:97], v[130:133], v[186:189], v[94:97]
	v_mfma_f32_16x16x32_bf16 v[90:93], v[138:141], v[186:189], v[90:93]
	v_mfma_f32_16x16x32_bf16 v[74:77], v[138:141], v[206:209], v[74:77]
	v_mfma_f32_16x16x32_bf16 v[78:81], v[130:133], v[206:209], v[78:81]
	v_mfma_f32_16x16x32_bf16 v[126:129], v[134:137], v[174:177], v[126:129]
	v_mfma_f32_16x16x32_bf16 v[122:125], v[142:145], v[174:177], v[122:125]
	v_mfma_f32_16x16x32_bf16 v[106:109], v[142:145], v[182:185], v[106:109]
	v_mfma_f32_16x16x32_bf16 v[110:113], v[134:137], v[182:185], v[110:113]
	v_mfma_f32_16x16x32_bf16 v[94:97], v[134:137], v[190:193], v[94:97]
	v_mfma_f32_16x16x32_bf16 v[90:93], v[142:145], v[190:193], v[90:93]
	v_mfma_f32_16x16x32_bf16 v[74:77], v[142:145], v[210:213], v[74:77]
	v_mfma_f32_16x16x32_bf16 v[78:81], v[134:137], v[210:213], v[78:81]
	v_mfma_f32_16x16x32_bf16 v[118:121], v[146:149], v[170:173], v[118:121]
	v_mfma_f32_16x16x32_bf16 v[114:117], v[154:157], v[170:173], v[114:117]
	v_mfma_f32_16x16x32_bf16 v[98:101], v[154:157], v[178:181], v[98:101]
	v_mfma_f32_16x16x32_bf16 v[102:105], v[146:149], v[178:181], v[102:105]
	v_mfma_f32_16x16x32_bf16 v[86:89], v[146:149], v[186:189], v[86:89]
	v_mfma_f32_16x16x32_bf16 v[82:85], v[154:157], v[186:189], v[82:85]
	v_mfma_f32_16x16x32_bf16 v[66:69], v[154:157], v[206:209], v[66:69]
	v_mfma_f32_16x16x32_bf16 v[70:73], v[146:149], v[206:209], v[70:73]
	v_mfma_f32_16x16x32_bf16 v[118:121], v[150:153], v[174:177], v[118:121]
	v_mfma_f32_16x16x32_bf16 v[114:117], v[166:169], v[174:177], v[114:117]
	v_mfma_f32_16x16x32_bf16 v[98:101], v[166:169], v[182:185], v[98:101]
	v_mfma_f32_16x16x32_bf16 v[102:105], v[150:153], v[182:185], v[102:105]
	v_mfma_f32_16x16x32_bf16 v[86:89], v[150:153], v[190:193], v[86:89]
	v_mfma_f32_16x16x32_bf16 v[82:85], v[166:169], v[190:193], v[82:85]
	v_mfma_f32_16x16x32_bf16 v[66:69], v[166:169], v[210:213], v[66:69]
	v_mfma_f32_16x16x32_bf16 v[70:73], v[150:153], v[210:213], v[70:73]
	s_barrier
	s_setprio 0
	s_add_i32 s30, s30, s39
	v_lshl_add_u64 v[202:203], s[20:21], 0, v[158:159]
	s_mov_b32 m0, s30
	ds_read_b128 v[170:173], v205 offset:16384
	ds_read_b128 v[174:177], v205 offset:17408
	ds_read_b128 v[178:181], v205 offset:18432
	ds_read_b128 v[182:185], v205 offset:19456
	ds_read_b128 v[186:189], v205 offset:20480
	ds_read_b128 v[190:193], v205 offset:21504
	ds_read_b128 v[206:209], v205 offset:22528
	ds_read_b128 v[210:213], v205 offset:23552
	global_load_lds_dwordx4 v[202:203], off
	s_add_i32 m0, s30, 0x2000
	s_add_u32 s30, s20, 0x80000
	v_lshl_add_u64 v[214:215], s[20:21], 0, v[160:161]
	s_addc_u32 s31, s21, 0
	s_add_i32 s42, s42, s39
	global_load_lds_dwordx4 v[214:215], off
	v_lshl_add_u64 v[216:217], s[30:31], 0, v[158:159]
	s_mov_b32 m0, s42
	v_lshl_add_u64 v[228:229], s[22:23], 0, v[160:161]
	global_load_lds_dwordx4 v[216:217], off
	v_lshl_add_u64 v[216:217], s[30:31], 0, v[160:161]
	s_add_i32 m0, s42, 0x2000
	s_nop 0
	global_load_lds_dwordx4 v[216:217], off
	v_lshl_add_u64 v[216:217], s[22:23], 0, v[158:159]
	s_mov_b32 m0, s87
	s_nop 0
	global_load_lds_dwordx4 v[216:217], off
	s_mov_b32 m0, s92
	s_nop 0
	global_load_lds_dwordx4 v[228:229], off
	s_waitcnt vmcnt(8)
	s_waitcnt lgkmcnt(0)
	s_setprio 1
	s_barrier
	v_mfma_f32_16x16x32_bf16 v[62:65], v[130:133], v[170:173], v[62:65]
	v_mfma_f32_16x16x32_bf16 v[58:61], v[138:141], v[170:173], v[58:61]
	v_mfma_f32_16x16x32_bf16 v[42:45], v[138:141], v[178:181], v[42:45]
	v_mfma_f32_16x16x32_bf16 v[46:49], v[130:133], v[178:181], v[46:49]
	v_mfma_f32_16x16x32_bf16 v[30:33], v[130:133], v[186:189], v[30:33]
	v_mfma_f32_16x16x32_bf16 v[26:29], v[138:141], v[186:189], v[26:29]
	v_mfma_f32_16x16x32_bf16 v[10:13], v[138:141], v[206:209], v[10:13]
	v_mfma_f32_16x16x32_bf16 v[14:17], v[130:133], v[206:209], v[14:17]
	v_mfma_f32_16x16x32_bf16 v[62:65], v[134:137], v[174:177], v[62:65]
	v_mfma_f32_16x16x32_bf16 v[58:61], v[142:145], v[174:177], v[58:61]
	v_mfma_f32_16x16x32_bf16 v[42:45], v[142:145], v[182:185], v[42:45]
	v_mfma_f32_16x16x32_bf16 v[46:49], v[134:137], v[182:185], v[46:49]
	v_mfma_f32_16x16x32_bf16 v[30:33], v[134:137], v[190:193], v[30:33]
	v_mfma_f32_16x16x32_bf16 v[26:29], v[142:145], v[190:193], v[26:29]
	v_mfma_f32_16x16x32_bf16 v[10:13], v[142:145], v[210:213], v[10:13]
	v_mfma_f32_16x16x32_bf16 v[14:17], v[134:137], v[210:213], v[14:17]
	v_mfma_f32_16x16x32_bf16 v[54:57], v[146:149], v[170:173], v[54:57]
	v_mfma_f32_16x16x32_bf16 v[50:53], v[154:157], v[170:173], v[50:53]
	v_mfma_f32_16x16x32_bf16 v[34:37], v[154:157], v[178:181], v[34:37]
	v_mfma_f32_16x16x32_bf16 v[38:41], v[146:149], v[178:181], v[38:41]
	v_mfma_f32_16x16x32_bf16 v[22:25], v[146:149], v[186:189], v[22:25]
	v_mfma_f32_16x16x32_bf16 v[18:21], v[154:157], v[186:189], v[18:21]
	v_mfma_f32_16x16x32_bf16 v[2:5], v[154:157], v[206:209], v[2:5]
	v_mfma_f32_16x16x32_bf16 v[6:9], v[146:149], v[206:209], v[6:9]
	v_mfma_f32_16x16x32_bf16 v[54:57], v[150:153], v[174:177], v[54:57]
	v_mfma_f32_16x16x32_bf16 v[50:53], v[166:169], v[174:177], v[50:53]
	v_mfma_f32_16x16x32_bf16 v[34:37], v[166:169], v[182:185], v[34:37]
	v_mfma_f32_16x16x32_bf16 v[38:41], v[150:153], v[182:185], v[38:41]
	v_mfma_f32_16x16x32_bf16 v[22:25], v[150:153], v[190:193], v[22:25]
	v_mfma_f32_16x16x32_bf16 v[18:21], v[166:169], v[190:193], v[18:21]
	v_mfma_f32_16x16x32_bf16 v[2:5], v[166:169], v[210:213], v[2:5]
	v_mfma_f32_16x16x32_bf16 v[6:9], v[150:153], v[210:213], v[6:9]
	s_barrier
	s_setprio 0
	s_add_i32 s30, 0, 0x18000
	s_add_i32 s31, 0, 0x1c000
	v_add_u32_e32 v142, s30, v204
	v_add_u32_e32 v166, s31, v204
	ds_read_b128 v[130:133], v142
	ds_read_b128 v[134:137], v142 offset:1024
	ds_read_b128 v[138:141], v142 offset:2048
	ds_read_b128 v[142:145], v142 offset:3072
	ds_read_b128 v[146:149], v166
	ds_read_b128 v[150:153], v166 offset:1024
	ds_read_b128 v[154:157], v166 offset:2048
	ds_read_b128 v[166:169], v166 offset:3072
	s_add_u32 s22, s22, 0x80000
	s_addc_u32 s23, s23, 0
	s_mov_b32 m0, s8
	v_lshl_add_u64 v[230:231], s[22:23], 0, v[158:159]
	ds_read_b128 v[170:173], v205 offset:32768
	ds_read_b128 v[174:177], v205 offset:33792
	ds_read_b128 v[178:181], v205 offset:34816
	ds_read_b128 v[182:185], v205 offset:35840
	ds_read_b128 v[186:189], v205 offset:36864
	ds_read_b128 v[190:193], v205 offset:37888
	ds_read_b128 v[206:209], v205 offset:38912
	ds_read_b128 v[210:213], v205 offset:39936
	global_load_lds_dwordx4 v[230:231], off
	v_lshl_add_u64 v[230:231], s[22:23], 0, v[160:161]
	s_mov_b32 m0, s9
	s_nop 0
	global_load_lds_dwordx4 v[230:231], off
	s_waitcnt vmcnt(8)
	s_waitcnt lgkmcnt(0)
	s_setprio 1
	s_barrier
	v_mfma_f32_16x16x32_bf16 v[126:129], v[130:133], v[170:173], v[126:129]
	v_mfma_f32_16x16x32_bf16 v[122:125], v[138:141], v[170:173], v[122:125]
	v_mfma_f32_16x16x32_bf16 v[106:109], v[138:141], v[178:181], v[106:109]
	v_mfma_f32_16x16x32_bf16 v[110:113], v[130:133], v[178:181], v[110:113]
	v_mfma_f32_16x16x32_bf16 v[94:97], v[130:133], v[186:189], v[94:97]
	v_mfma_f32_16x16x32_bf16 v[90:93], v[138:141], v[186:189], v[90:93]
	v_mfma_f32_16x16x32_bf16 v[74:77], v[138:141], v[206:209], v[74:77]
	v_mfma_f32_16x16x32_bf16 v[78:81], v[130:133], v[206:209], v[78:81]
	v_mfma_f32_16x16x32_bf16 v[126:129], v[134:137], v[174:177], v[126:129]
	v_mfma_f32_16x16x32_bf16 v[122:125], v[142:145], v[174:177], v[122:125]
	v_mfma_f32_16x16x32_bf16 v[106:109], v[142:145], v[182:185], v[106:109]
	v_mfma_f32_16x16x32_bf16 v[110:113], v[134:137], v[182:185], v[110:113]
	v_mfma_f32_16x16x32_bf16 v[94:97], v[134:137], v[190:193], v[94:97]
	v_mfma_f32_16x16x32_bf16 v[90:93], v[142:145], v[190:193], v[90:93]
	v_mfma_f32_16x16x32_bf16 v[74:77], v[142:145], v[210:213], v[74:77]
	v_mfma_f32_16x16x32_bf16 v[78:81], v[134:137], v[210:213], v[78:81]
	v_mfma_f32_16x16x32_bf16 v[118:121], v[146:149], v[170:173], v[118:121]
	v_mfma_f32_16x16x32_bf16 v[114:117], v[154:157], v[170:173], v[114:117]
	v_mfma_f32_16x16x32_bf16 v[98:101], v[154:157], v[178:181], v[98:101]
	v_mfma_f32_16x16x32_bf16 v[102:105], v[146:149], v[178:181], v[102:105]
	v_mfma_f32_16x16x32_bf16 v[86:89], v[146:149], v[186:189], v[86:89]
	v_mfma_f32_16x16x32_bf16 v[82:85], v[154:157], v[186:189], v[82:85]
	v_mfma_f32_16x16x32_bf16 v[66:69], v[154:157], v[206:209], v[66:69]
	v_mfma_f32_16x16x32_bf16 v[70:73], v[146:149], v[206:209], v[70:73]
	v_mfma_f32_16x16x32_bf16 v[118:121], v[150:153], v[174:177], v[118:121]
	v_mfma_f32_16x16x32_bf16 v[114:117], v[166:169], v[174:177], v[114:117]
	v_mfma_f32_16x16x32_bf16 v[98:101], v[166:169], v[182:185], v[98:101]
	v_mfma_f32_16x16x32_bf16 v[102:105], v[150:153], v[182:185], v[102:105]
	v_mfma_f32_16x16x32_bf16 v[86:89], v[150:153], v[190:193], v[86:89]
	v_mfma_f32_16x16x32_bf16 v[82:85], v[166:169], v[190:193], v[82:85]
	v_mfma_f32_16x16x32_bf16 v[66:69], v[166:169], v[210:213], v[66:69]
	v_mfma_f32_16x16x32_bf16 v[70:73], v[150:153], v[210:213], v[70:73]
	s_barrier
	s_setprio 0
	s_add_i32 s22, s30, s39
	v_lshl_add_u64 v[202:203], v[202:203], 0, s[10:11]
	s_mov_b32 m0, s22
	ds_read_b128 v[170:173], v205 offset:49152
	ds_read_b128 v[174:177], v205 offset:50176
	ds_read_b128 v[178:181], v205 offset:51200
	ds_read_b128 v[182:185], v205 offset:52224
	ds_read_b128 v[186:189], v205 offset:53248
	ds_read_b128 v[190:193], v205 offset:54272
	ds_read_b128 v[206:209], v205 offset:55296
	ds_read_b128 v[210:213], v205 offset:56320
	global_load_lds_dwordx4 v[202:203], off
	s_add_i32 m0, s22, 0x2000
	s_add_u32 s20, s20, 0x80080
	v_lshl_add_u64 v[202:203], v[214:215], 0, s[10:11]
	s_addc_u32 s21, s21, 0
	s_add_i32 s22, s31, s39
	global_load_lds_dwordx4 v[202:203], off
	v_lshl_add_u64 v[202:203], s[20:21], 0, v[158:159]
	s_mov_b32 m0, s22
	s_nop 0
	global_load_lds_dwordx4 v[202:203], off
	v_lshl_add_u64 v[202:203], s[20:21], 0, v[160:161]
	s_add_i32 m0, s22, 0x2000
	s_nop 0
	global_load_lds_dwordx4 v[202:203], off
	v_lshl_add_u64 v[202:203], v[216:217], 0, s[10:11]
	s_mov_b32 m0, s56
	s_nop 0
	global_load_lds_dwordx4 v[202:203], off
	v_lshl_add_u64 v[202:203], v[228:229], 0, s[10:11]
	s_mov_b32 m0, s57
	s_nop 0
	global_load_lds_dwordx4 v[202:203], off
	s_waitcnt vmcnt(8)
	s_waitcnt lgkmcnt(0)
	s_setprio 1
	s_barrier
	v_mfma_f32_16x16x32_bf16 v[62:65], v[130:133], v[170:173], v[62:65]
	v_mfma_f32_16x16x32_bf16 v[58:61], v[138:141], v[170:173], v[58:61]
	v_mfma_f32_16x16x32_bf16 v[42:45], v[138:141], v[178:181], v[42:45]
	v_mfma_f32_16x16x32_bf16 v[46:49], v[130:133], v[178:181], v[46:49]
	v_mfma_f32_16x16x32_bf16 v[30:33], v[130:133], v[186:189], v[30:33]
	v_mfma_f32_16x16x32_bf16 v[26:29], v[138:141], v[186:189], v[26:29]
	v_mfma_f32_16x16x32_bf16 v[10:13], v[138:141], v[206:209], v[10:13]
	v_mfma_f32_16x16x32_bf16 v[14:17], v[130:133], v[206:209], v[14:17]
	v_mfma_f32_16x16x32_bf16 v[62:65], v[134:137], v[174:177], v[62:65]
	v_mfma_f32_16x16x32_bf16 v[58:61], v[142:145], v[174:177], v[58:61]
	v_mfma_f32_16x16x32_bf16 v[42:45], v[142:145], v[182:185], v[42:45]
	v_mfma_f32_16x16x32_bf16 v[46:49], v[134:137], v[182:185], v[46:49]
	v_mfma_f32_16x16x32_bf16 v[30:33], v[134:137], v[190:193], v[30:33]
	v_mfma_f32_16x16x32_bf16 v[26:29], v[142:145], v[190:193], v[26:29]
	v_mfma_f32_16x16x32_bf16 v[10:13], v[142:145], v[210:213], v[10:13]
	v_mfma_f32_16x16x32_bf16 v[14:17], v[134:137], v[210:213], v[14:17]
	v_mfma_f32_16x16x32_bf16 v[54:57], v[146:149], v[170:173], v[54:57]
	v_mfma_f32_16x16x32_bf16 v[50:53], v[154:157], v[170:173], v[50:53]
	v_mfma_f32_16x16x32_bf16 v[34:37], v[154:157], v[178:181], v[34:37]
	v_mfma_f32_16x16x32_bf16 v[38:41], v[146:149], v[178:181], v[38:41]
	v_mfma_f32_16x16x32_bf16 v[22:25], v[146:149], v[186:189], v[22:25]
	v_mfma_f32_16x16x32_bf16 v[18:21], v[154:157], v[186:189], v[18:21]
	v_mfma_f32_16x16x32_bf16 v[2:5], v[154:157], v[206:209], v[2:5]
	v_mfma_f32_16x16x32_bf16 v[6:9], v[146:149], v[206:209], v[6:9]
	v_mfma_f32_16x16x32_bf16 v[54:57], v[150:153], v[174:177], v[54:57]
	v_mfma_f32_16x16x32_bf16 v[50:53], v[166:169], v[174:177], v[50:53]
	v_mfma_f32_16x16x32_bf16 v[34:37], v[166:169], v[182:185], v[34:37]
	v_mfma_f32_16x16x32_bf16 v[38:41], v[150:153], v[182:185], v[38:41]
	v_mfma_f32_16x16x32_bf16 v[22:25], v[150:153], v[190:193], v[22:25]
	v_mfma_f32_16x16x32_bf16 v[18:21], v[166:169], v[190:193], v[18:21]
	v_mfma_f32_16x16x32_bf16 v[2:5], v[166:169], v[210:213], v[2:5]
	v_mfma_f32_16x16x32_bf16 v[6:9], v[150:153], v[210:213], v[6:9]
	s_barrier
	s_setprio 0
	s_add_i32 s29, s29, 2
	s_add_u32 s18, s18, 0x100
	s_addc_u32 s19, s19, 0
	s_add_u32 s27, s27, 0x100
	s_addc_u32 s28, s28, 0
	s_cmp_gt_u32 s29, 29
	s_cbranch_scc0 .LBB0_364
	s_and_b64 vcc, exec, s[58:59]
	s_cbranch_vccz .LBB0_367
	s_barrier

.LBB0_986:
	s_add_u32 s24, s22, 0x100
	s_addc_u32 s25, s23, 0
	s_add_i32 s62, 0, 0x10000
	s_cmp_eq_u32 s61, 28
	s_cselect_b32 s29, s17, s25
	s_cselect_b32 s28, s58, s24
	v_add_u32_e32 v138, s62, v140
	s_cselect_b32 s27, s19, s60
	s_cselect_b32 s26, s18, s59
	s_add_i32 s63, 0, 0x14000
	ds_read_b128 v[142:145], v138
	ds_read_b128 v[146:149], v138 offset:1024
	ds_read_b128 v[150:153], v138 offset:2048
	ds_read_b128 v[154:157], v138 offset:3072
	v_add_u32_e32 v138, s63, v140
	ds_read_b128 v[158:161], v138
	ds_read_b128 v[162:165], v138 offset:1024
	ds_read_b128 v[166:169], v138 offset:2048
	ds_read_b128 v[170:173], v138 offset:3072
	v_lshl_add_u64 v[138:139], s[22:23], 0, v[134:135]
	s_add_i32 m0, s47, 0xc000
	ds_read_b128 v[174:177], v141
	ds_read_b128 v[178:181], v141 offset:1024
	ds_read_b128 v[182:185], v141 offset:2048
	ds_read_b128 v[186:189], v141 offset:3072
	ds_read_b128 v[190:193], v141 offset:4096
	ds_read_b128 v[202:205], v141 offset:5120
	ds_read_b128 v[206:209], v141 offset:6144
	ds_read_b128 v[210:213], v141 offset:7168
	global_load_lds_dwordx4 v[138:139], off
	v_lshl_add_u64 v[138:139], s[22:23], 0, v[136:137]
	s_add_i32 m0, s47, 0xe000
	s_nop 0
	global_load_lds_dwordx4 v[138:139], off
	s_waitcnt vmcnt(8)
	s_waitcnt lgkmcnt(0)
	s_setprio 1
	s_barrier
	v_mfma_f32_16x16x32_bf16 v[126:129], v[142:145], v[174:177], v[126:129]
	v_mfma_f32_16x16x32_bf16 v[122:125], v[150:153], v[174:177], v[122:125]
	v_mfma_f32_16x16x32_bf16 v[110:113], v[150:153], v[182:185], v[110:113]
	v_mfma_f32_16x16x32_bf16 v[118:121], v[142:145], v[182:185], v[118:121]
	v_mfma_f32_16x16x32_bf16 v[102:105], v[142:145], v[190:193], v[102:105]
	v_mfma_f32_16x16x32_bf16 v[94:97], v[150:153], v[190:193], v[94:97]
	v_mfma_f32_16x16x32_bf16 v[78:81], v[150:153], v[206:209], v[78:81]
	v_mfma_f32_16x16x32_bf16 v[86:89], v[142:145], v[206:209], v[86:89]
	v_mfma_f32_16x16x32_bf16 v[126:129], v[146:149], v[178:181], v[126:129]
	v_mfma_f32_16x16x32_bf16 v[122:125], v[154:157], v[178:181], v[122:125]
	v_mfma_f32_16x16x32_bf16 v[110:113], v[154:157], v[186:189], v[110:113]
	v_mfma_f32_16x16x32_bf16 v[118:121], v[146:149], v[186:189], v[118:121]
	v_mfma_f32_16x16x32_bf16 v[102:105], v[146:149], v[202:205], v[102:105]
	v_mfma_f32_16x16x32_bf16 v[94:97], v[154:157], v[202:205], v[94:97]
	v_mfma_f32_16x16x32_bf16 v[78:81], v[154:157], v[210:213], v[78:81]
	v_mfma_f32_16x16x32_bf16 v[86:89], v[146:149], v[210:213], v[86:89]
	v_mfma_f32_16x16x32_bf16 v[114:117], v[158:161], v[174:177], v[114:117]
	v_mfma_f32_16x16x32_bf16 v[106:109], v[166:169], v[174:177], v[106:109]
	v_mfma_f32_16x16x32_bf16 v[90:93], v[166:169], v[182:185], v[90:93]
	v_mfma_f32_16x16x32_bf16 v[98:101], v[158:161], v[182:185], v[98:101]
	v_mfma_f32_16x16x32_bf16 v[82:85], v[158:161], v[190:193], v[82:85]
	v_mfma_f32_16x16x32_bf16 v[74:77], v[166:169], v[190:193], v[74:77]
	v_mfma_f32_16x16x32_bf16 v[66:69], v[166:169], v[206:209], v[66:69]
	v_mfma_f32_16x16x32_bf16 v[70:73], v[158:161], v[206:209], v[70:73]
	v_mfma_f32_16x16x32_bf16 v[114:117], v[162:165], v[178:181], v[114:117]
	v_mfma_f32_16x16x32_bf16 v[106:109], v[170:173], v[178:181], v[106:109]
	v_mfma_f32_16x16x32_bf16 v[90:93], v[170:173], v[186:189], v[90:93]
	v_mfma_f32_16x16x32_bf16 v[98:101], v[162:165], v[186:189], v[98:101]
	v_mfma_f32_16x16x32_bf16 v[82:85], v[162:165], v[202:205], v[82:85]
	v_mfma_f32_16x16x32_bf16 v[74:77], v[170:173], v[202:205], v[74:77]
	v_mfma_f32_16x16x32_bf16 v[66:69], v[170:173], v[210:213], v[66:69]
	v_mfma_f32_16x16x32_bf16 v[70:73], v[162:165], v[210:213], v[70:73]
	s_barrier
	s_setprio 0
	s_add_i32 s22, s62, s36
	v_lshl_add_u64 v[138:139], s[26:27], 0, v[132:133]
	s_mov_b32 m0, s22
	ds_read_b128 v[174:177], v141 offset:16384
	ds_read_b128 v[178:181], v141 offset:17408
	ds_read_b128 v[182:185], v141 offset:18432
	ds_read_b128 v[186:189], v141 offset:19456
	ds_read_b128 v[190:193], v141 offset:20480
	ds_read_b128 v[202:205], v141 offset:21504
	ds_read_b128 v[206:209], v141 offset:22528
	ds_read_b128 v[210:213], v141 offset:23552
	global_load_lds_dwordx4 v[138:139], off
	s_add_i32 m0, s22, 0x2000
	s_add_u32 s22, s26, 0x80000
	v_lshl_add_u64 v[214:215], s[26:27], 0, v[130:131]
	s_addc_u32 s23, s27, 0
	s_add_i32 s62, s63, s36
	global_load_lds_dwordx4 v[214:215], off
	v_lshl_add_u64 v[216:217], s[22:23], 0, v[132:133]
	s_mov_b32 m0, s62
	v_lshl_add_u64 v[228:229], s[28:29], 0, v[130:131]
	global_load_lds_dwordx4 v[216:217], off
	v_lshl_add_u64 v[216:217], s[22:23], 0, v[130:131]
	s_add_i32 m0, s62, 0x2000
	s_nop 0
	global_load_lds_dwordx4 v[216:217], off
	v_lshl_add_u64 v[216:217], s[28:29], 0, v[132:133]
	s_mov_b32 m0, s47
	s_nop 0
	global_load_lds_dwordx4 v[216:217], off
	s_mov_b32 m0, s48
	s_nop 0
	global_load_lds_dwordx4 v[228:229], off
	s_waitcnt vmcnt(8)
	s_waitcnt lgkmcnt(0)
	s_setprio 1
	s_barrier
	v_mfma_f32_16x16x32_bf16 v[62:65], v[142:145], v[174:177], v[62:65]
	v_mfma_f32_16x16x32_bf16 v[58:61], v[150:153], v[174:177], v[58:61]
	v_mfma_f32_16x16x32_bf16 v[46:49], v[150:153], v[182:185], v[46:49]
	v_mfma_f32_16x16x32_bf16 v[54:57], v[142:145], v[182:185], v[54:57]
	v_mfma_f32_16x16x32_bf16 v[38:41], v[142:145], v[190:193], v[38:41]
	v_mfma_f32_16x16x32_bf16 v[30:33], v[150:153], v[190:193], v[30:33]
	v_mfma_f32_16x16x32_bf16 v[14:17], v[150:153], v[206:209], v[14:17]
	v_mfma_f32_16x16x32_bf16 v[22:25], v[142:145], v[206:209], v[22:25]
	v_mfma_f32_16x16x32_bf16 v[62:65], v[146:149], v[178:181], v[62:65]
	v_mfma_f32_16x16x32_bf16 v[58:61], v[154:157], v[178:181], v[58:61]
	v_mfma_f32_16x16x32_bf16 v[46:49], v[154:157], v[186:189], v[46:49]
	v_mfma_f32_16x16x32_bf16 v[54:57], v[146:149], v[186:189], v[54:57]
	v_mfma_f32_16x16x32_bf16 v[38:41], v[146:149], v[202:205], v[38:41]
	v_mfma_f32_16x16x32_bf16 v[30:33], v[154:157], v[202:205], v[30:33]
	v_mfma_f32_16x16x32_bf16 v[14:17], v[154:157], v[210:213], v[14:17]
	v_mfma_f32_16x16x32_bf16 v[22:25], v[146:149], v[210:213], v[22:25]
	v_mfma_f32_16x16x32_bf16 v[50:53], v[158:161], v[174:177], v[50:53]
	v_mfma_f32_16x16x32_bf16 v[42:45], v[166:169], v[174:177], v[42:45]
	v_mfma_f32_16x16x32_bf16 v[26:29], v[166:169], v[182:185], v[26:29]
	v_mfma_f32_16x16x32_bf16 v[34:37], v[158:161], v[182:185], v[34:37]
	v_mfma_f32_16x16x32_bf16 v[18:21], v[158:161], v[190:193], v[18:21]
	v_mfma_f32_16x16x32_bf16 v[10:13], v[166:169], v[190:193], v[10:13]
	v_mfma_f32_16x16x32_bf16 v[2:5], v[166:169], v[206:209], v[2:5]
	v_mfma_f32_16x16x32_bf16 v[6:9], v[158:161], v[206:209], v[6:9]
	v_mfma_f32_16x16x32_bf16 v[50:53], v[162:165], v[178:181], v[50:53]
	v_mfma_f32_16x16x32_bf16 v[42:45], v[170:173], v[178:181], v[42:45]
	v_mfma_f32_16x16x32_bf16 v[26:29], v[170:173], v[186:189], v[26:29]
	v_mfma_f32_16x16x32_bf16 v[34:37], v[162:165], v[186:189], v[34:37]
	v_mfma_f32_16x16x32_bf16 v[18:21], v[162:165], v[202:205], v[18:21]
	v_mfma_f32_16x16x32_bf16 v[10:13], v[170:173], v[202:205], v[10:13]
	v_mfma_f32_16x16x32_bf16 v[2:5], v[170:173], v[210:213], v[2:5]
	v_mfma_f32_16x16x32_bf16 v[6:9], v[162:165], v[210:213], v[6:9]
	s_barrier
	s_setprio 0
	s_add_i32 s62, 0, 0x18000
	s_add_i32 s63, 0, 0x1c000
	v_add_u32_e32 v154, s62, v140
	v_add_u32_e32 v170, s63, v140
	ds_read_b128 v[142:145], v154
	ds_read_b128 v[146:149], v154 offset:1024
	ds_read_b128 v[150:153], v154 offset:2048
	ds_read_b128 v[154:157], v154 offset:3072
	ds_read_b128 v[158:161], v170
	ds_read_b128 v[162:165], v170 offset:1024
	ds_read_b128 v[166:169], v170 offset:2048
	ds_read_b128 v[170:173], v170 offset:3072
	s_add_u32 s22, s28, 0x80000
	s_addc_u32 s23, s29, 0
	s_mov_b32 m0, s49
	v_lshl_add_u64 v[230:231], s[22:23], 0, v[132:133]
	ds_read_b128 v[174:177], v141 offset:32768
	ds_read_b128 v[178:181], v141 offset:33792
	ds_read_b128 v[182:185], v141 offset:34816
	ds_read_b128 v[186:189], v141 offset:35840
	ds_read_b128 v[190:193], v141 offset:36864
	ds_read_b128 v[202:205], v141 offset:37888
	ds_read_b128 v[206:209], v141 offset:38912
	ds_read_b128 v[210:213], v141 offset:39936
	global_load_lds_dwordx4 v[230:231], off
	v_lshl_add_u64 v[230:231], s[22:23], 0, v[130:131]
	s_mov_b32 m0, s50
	s_nop 0
	global_load_lds_dwordx4 v[230:231], off
	s_waitcnt vmcnt(8)
	s_waitcnt lgkmcnt(0)
	s_setprio 1
	s_barrier
	v_mfma_f32_16x16x32_bf16 v[126:129], v[142:145], v[174:177], v[126:129]
	v_mfma_f32_16x16x32_bf16 v[122:125], v[150:153], v[174:177], v[122:125]
	v_mfma_f32_16x16x32_bf16 v[110:113], v[150:153], v[182:185], v[110:113]
	v_mfma_f32_16x16x32_bf16 v[118:121], v[142:145], v[182:185], v[118:121]
	v_mfma_f32_16x16x32_bf16 v[102:105], v[142:145], v[190:193], v[102:105]
	v_mfma_f32_16x16x32_bf16 v[94:97], v[150:153], v[190:193], v[94:97]
	v_mfma_f32_16x16x32_bf16 v[78:81], v[150:153], v[206:209], v[78:81]
	v_mfma_f32_16x16x32_bf16 v[86:89], v[142:145], v[206:209], v[86:89]
	v_mfma_f32_16x16x32_bf16 v[126:129], v[146:149], v[178:181], v[126:129]
	v_mfma_f32_16x16x32_bf16 v[122:125], v[154:157], v[178:181], v[122:125]
	v_mfma_f32_16x16x32_bf16 v[110:113], v[154:157], v[186:189], v[110:113]
	v_mfma_f32_16x16x32_bf16 v[118:121], v[146:149], v[186:189], v[118:121]
	v_mfma_f32_16x16x32_bf16 v[102:105], v[146:149], v[202:205], v[102:105]
	v_mfma_f32_16x16x32_bf16 v[94:97], v[154:157], v[202:205], v[94:97]
	v_mfma_f32_16x16x32_bf16 v[78:81], v[154:157], v[210:213], v[78:81]
	v_mfma_f32_16x16x32_bf16 v[86:89], v[146:149], v[210:213], v[86:89]
	v_mfma_f32_16x16x32_bf16 v[114:117], v[158:161], v[174:177], v[114:117]
	v_mfma_f32_16x16x32_bf16 v[106:109], v[166:169], v[174:177], v[106:109]
	v_mfma_f32_16x16x32_bf16 v[90:93], v[166:169], v[182:185], v[90:93]
	v_mfma_f32_16x16x32_bf16 v[98:101], v[158:161], v[182:185], v[98:101]
	v_mfma_f32_16x16x32_bf16 v[82:85], v[158:161], v[190:193], v[82:85]
	v_mfma_f32_16x16x32_bf16 v[74:77], v[166:169], v[190:193], v[74:77]
	v_mfma_f32_16x16x32_bf16 v[66:69], v[166:169], v[206:209], v[66:69]
	v_mfma_f32_16x16x32_bf16 v[70:73], v[158:161], v[206:209], v[70:73]
	v_mfma_f32_16x16x32_bf16 v[114:117], v[162:165], v[178:181], v[114:117]
	v_mfma_f32_16x16x32_bf16 v[106:109], v[170:173], v[178:181], v[106:109]
	v_mfma_f32_16x16x32_bf16 v[90:93], v[170:173], v[186:189], v[90:93]
	v_mfma_f32_16x16x32_bf16 v[98:101], v[162:165], v[186:189], v[98:101]
	v_mfma_f32_16x16x32_bf16 v[82:85], v[162:165], v[202:205], v[82:85]
	v_mfma_f32_16x16x32_bf16 v[74:77], v[170:173], v[202:205], v[74:77]
	v_mfma_f32_16x16x32_bf16 v[66:69], v[170:173], v[210:213], v[66:69]
	v_mfma_f32_16x16x32_bf16 v[70:73], v[162:165], v[210:213], v[70:73]
	s_barrier
	s_setprio 0
	s_add_i32 s22, s62, s36
	v_lshl_add_u64 v[138:139], v[138:139], 0, s[10:11]
	s_mov_b32 m0, s22
	ds_read_b128 v[174:177], v141 offset:49152
	ds_read_b128 v[178:181], v141 offset:50176
	ds_read_b128 v[182:185], v141 offset:51200
	ds_read_b128 v[186:189], v141 offset:52224
	ds_read_b128 v[190:193], v141 offset:53248
	ds_read_b128 v[202:205], v141 offset:54272
	ds_read_b128 v[206:209], v141 offset:55296
	ds_read_b128 v[210:213], v141 offset:56320
	global_load_lds_dwordx4 v[138:139], off
	s_add_i32 m0, s22, 0x2000
	s_add_u32 s22, s26, 0x80080
	v_lshl_add_u64 v[138:139], v[214:215], 0, s[10:11]
	s_addc_u32 s23, s27, 0
	s_add_i32 s26, s63, s36
	global_load_lds_dwordx4 v[138:139], off
	v_lshl_add_u64 v[138:139], s[22:23], 0, v[132:133]
	s_mov_b32 m0, s26
	s_nop 0
	global_load_lds_dwordx4 v[138:139], off
	v_lshl_add_u64 v[138:139], s[22:23], 0, v[130:131]
	s_add_i32 m0, s26, 0x2000
	s_nop 0
	global_load_lds_dwordx4 v[138:139], off
	v_lshl_add_u64 v[138:139], v[216:217], 0, s[10:11]
	s_mov_b32 m0, s51
	s_nop 0
	global_load_lds_dwordx4 v[138:139], off
	v_lshl_add_u64 v[138:139], v[228:229], 0, s[10:11]
	s_mov_b32 m0, s52
	s_nop 0
	global_load_lds_dwordx4 v[138:139], off
	s_waitcnt vmcnt(8)
	s_waitcnt lgkmcnt(0)
	s_setprio 1
	s_barrier
	v_mfma_f32_16x16x32_bf16 v[62:65], v[142:145], v[174:177], v[62:65]
	v_mfma_f32_16x16x32_bf16 v[58:61], v[150:153], v[174:177], v[58:61]
	v_mfma_f32_16x16x32_bf16 v[46:49], v[150:153], v[182:185], v[46:49]
	v_mfma_f32_16x16x32_bf16 v[54:57], v[142:145], v[182:185], v[54:57]
	v_mfma_f32_16x16x32_bf16 v[38:41], v[142:145], v[190:193], v[38:41]
	v_mfma_f32_16x16x32_bf16 v[30:33], v[150:153], v[190:193], v[30:33]
	v_mfma_f32_16x16x32_bf16 v[14:17], v[150:153], v[206:209], v[14:17]
	v_mfma_f32_16x16x32_bf16 v[22:25], v[142:145], v[206:209], v[22:25]
	v_mfma_f32_16x16x32_bf16 v[62:65], v[146:149], v[178:181], v[62:65]
	v_mfma_f32_16x16x32_bf16 v[58:61], v[154:157], v[178:181], v[58:61]
	v_mfma_f32_16x16x32_bf16 v[46:49], v[154:157], v[186:189], v[46:49]
	v_mfma_f32_16x16x32_bf16 v[54:57], v[146:149], v[186:189], v[54:57]
	v_mfma_f32_16x16x32_bf16 v[38:41], v[146:149], v[202:205], v[38:41]
	v_mfma_f32_16x16x32_bf16 v[30:33], v[154:157], v[202:205], v[30:33]
	v_mfma_f32_16x16x32_bf16 v[14:17], v[154:157], v[210:213], v[14:17]
	v_mfma_f32_16x16x32_bf16 v[22:25], v[146:149], v[210:213], v[22:25]
	v_mfma_f32_16x16x32_bf16 v[50:53], v[158:161], v[174:177], v[50:53]
	v_mfma_f32_16x16x32_bf16 v[42:45], v[166:169], v[174:177], v[42:45]
	v_mfma_f32_16x16x32_bf16 v[26:29], v[166:169], v[182:185], v[26:29]
	v_mfma_f32_16x16x32_bf16 v[34:37], v[158:161], v[182:185], v[34:37]
	v_mfma_f32_16x16x32_bf16 v[18:21], v[158:161], v[190:193], v[18:21]
	v_mfma_f32_16x16x32_bf16 v[10:13], v[166:169], v[190:193], v[10:13]
	v_mfma_f32_16x16x32_bf16 v[2:5], v[166:169], v[206:209], v[2:5]
	v_mfma_f32_16x16x32_bf16 v[6:9], v[158:161], v[206:209], v[6:9]
	v_mfma_f32_16x16x32_bf16 v[50:53], v[162:165], v[178:181], v[50:53]
	v_mfma_f32_16x16x32_bf16 v[42:45], v[170:173], v[178:181], v[42:45]
	v_mfma_f32_16x16x32_bf16 v[26:29], v[170:173], v[186:189], v[26:29]
	v_mfma_f32_16x16x32_bf16 v[34:37], v[162:165], v[186:189], v[34:37]
	v_mfma_f32_16x16x32_bf16 v[18:21], v[162:165], v[202:205], v[18:21]
	v_mfma_f32_16x16x32_bf16 v[10:13], v[170:173], v[202:205], v[10:13]
	v_mfma_f32_16x16x32_bf16 v[2:5], v[170:173], v[210:213], v[2:5]
	v_mfma_f32_16x16x32_bf16 v[6:9], v[162:165], v[210:213], v[6:9]
	s_barrier
	s_setprio 0
	s_add_i32 s61, s61, 2
	s_add_u32 s59, s59, 0x100
	s_addc_u32 s60, s60, 0
	s_cmp_gt_u32 s61, 29
	s_mov_b64 s[22:23], s[24:25]
	s_cbranch_scc0 .LBB0_986
	s_and_b64 vcc, exec, s[14:15]
	s_cbranch_vccz .LBB0_989
	s_barrier

.LBB0_1002:
	s_add_i32 s36, s21, 0x100
	s_and_b64 s[30:31], s[28:29], exec
	s_cselect_b32 s31, 0, s36
	s_cselect_b32 s30, 0, 0
	s_add_u32 s36, s8, s31
	s_addc_u32 s37, s9, s30
	s_add_u32 s30, s24, s21
	s_addc_u32 s31, s25, 0
	s_add_u32 s30, s30, 0x100
	s_addc_u32 s31, s31, 0
	s_add_i32 s71, 0, 0x10000
	s_and_b64 s[28:29], s[28:29], exec
	s_cselect_b32 s39, s19, s31
	s_cselect_b32 s38, s18, s30
	s_add_i32 s29, 0, 0x14000
	s_add_u32 s21, s44, s21
	s_addc_u32 s28, s45, 0
	s_add_u32 s48, s21, 0x17110080
	s_addc_u32 s49, s28, 0
	s_add_i32 s70, s71, s52
	s_add_i32 m0, s53, 0xc000
	s_add_i32 s73, s53, 0xe000
	s_add_i32 s67, s70, 0x2000
	v_add_u32_e32 v134, s71, v136
	s_add_u32 s46, s38, 0x10000
	ds_read_b128 v[138:141], v134
	ds_read_b128 v[142:145], v134 offset:1024
	ds_read_b128 v[146:149], v134 offset:2048
	ds_read_b128 v[150:153], v134 offset:3072
	v_add_u32_e32 v134, s29, v136
	s_addc_u32 s47, s39, 0
	s_add_i32 s69, s29, s52
	ds_read_b128 v[154:157], v134
	ds_read_b128 v[158:161], v134 offset:1024
	ds_read_b128 v[162:165], v134 offset:2048
	ds_read_b128 v[166:169], v134 offset:3072
	s_add_i32 s68, s69, 0x2000
	s_add_i32 s66, 0, 0x18000
	s_add_i32 s65, 0, 0x1c000
	s_add_u32 s30, s36, 0x10000
	s_addc_u32 s31, s37, 0
	s_add_i32 s64, s66, s52
	s_add_i32 s21, s64, 0x2000
	s_add_u32 s28, s38, 0x10080
	s_addc_u32 s29, s39, 0
	s_add_i32 s72, s65, s52
	s_add_i32 s71, s72, 0x2000
	v_lshl_add_u64 v[134:135], s[48:49], 0, v[132:133]
	ds_read_b128 v[170:173], v137
	ds_read_b128 v[174:177], v137 offset:1024
	ds_read_b128 v[178:181], v137 offset:2048
	ds_read_b128 v[182:185], v137 offset:3072
	ds_read_b128 v[186:189], v137 offset:4096
	ds_read_b128 v[190:193], v137 offset:5120
	ds_read_b128 v[202:205], v137 offset:6144
	ds_read_b128 v[206:209], v137 offset:7168
	global_load_lds_dwordx4 v[134:135], off
	v_lshl_add_u64 v[134:135], s[48:49], 0, v[130:131]
	s_mov_b32 m0, s73
	s_nop 0
	global_load_lds_dwordx4 v[134:135], off
	s_waitcnt vmcnt(8)
	s_waitcnt lgkmcnt(0)
	s_setprio 1
	s_barrier
	v_mfma_f32_16x16x32_bf16 v[126:129], v[138:141], v[170:173], v[126:129]
	v_mfma_f32_16x16x32_bf16 v[122:125], v[146:149], v[170:173], v[122:125]
	v_mfma_f32_16x16x32_bf16 v[110:113], v[146:149], v[178:181], v[110:113]
	v_mfma_f32_16x16x32_bf16 v[118:121], v[138:141], v[178:181], v[118:121]
	v_mfma_f32_16x16x32_bf16 v[102:105], v[138:141], v[186:189], v[102:105]
	v_mfma_f32_16x16x32_bf16 v[94:97], v[146:149], v[186:189], v[94:97]
	v_mfma_f32_16x16x32_bf16 v[78:81], v[146:149], v[202:205], v[78:81]
	v_mfma_f32_16x16x32_bf16 v[86:89], v[138:141], v[202:205], v[86:89]
	v_mfma_f32_16x16x32_bf16 v[126:129], v[142:145], v[174:177], v[126:129]
	v_mfma_f32_16x16x32_bf16 v[122:125], v[150:153], v[174:177], v[122:125]
	v_mfma_f32_16x16x32_bf16 v[110:113], v[150:153], v[182:185], v[110:113]
	v_mfma_f32_16x16x32_bf16 v[118:121], v[142:145], v[182:185], v[118:121]
	v_mfma_f32_16x16x32_bf16 v[102:105], v[142:145], v[190:193], v[102:105]
	v_mfma_f32_16x16x32_bf16 v[94:97], v[150:153], v[190:193], v[94:97]
	v_mfma_f32_16x16x32_bf16 v[78:81], v[150:153], v[206:209], v[78:81]
	v_mfma_f32_16x16x32_bf16 v[86:89], v[142:145], v[206:209], v[86:89]
	v_mfma_f32_16x16x32_bf16 v[114:117], v[154:157], v[170:173], v[114:117]
	v_mfma_f32_16x16x32_bf16 v[106:109], v[162:165], v[170:173], v[106:109]
	v_mfma_f32_16x16x32_bf16 v[90:93], v[162:165], v[178:181], v[90:93]
	v_mfma_f32_16x16x32_bf16 v[98:101], v[154:157], v[178:181], v[98:101]
	v_mfma_f32_16x16x32_bf16 v[82:85], v[154:157], v[186:189], v[82:85]
	v_mfma_f32_16x16x32_bf16 v[74:77], v[162:165], v[186:189], v[74:77]
	v_mfma_f32_16x16x32_bf16 v[66:69], v[162:165], v[202:205], v[66:69]
	v_mfma_f32_16x16x32_bf16 v[70:73], v[154:157], v[202:205], v[70:73]
	v_mfma_f32_16x16x32_bf16 v[114:117], v[158:161], v[174:177], v[114:117]
	v_mfma_f32_16x16x32_bf16 v[106:109], v[166:169], v[174:177], v[106:109]
	v_mfma_f32_16x16x32_bf16 v[90:93], v[166:169], v[182:185], v[90:93]
	v_mfma_f32_16x16x32_bf16 v[98:101], v[158:161], v[182:185], v[98:101]
	v_mfma_f32_16x16x32_bf16 v[82:85], v[158:161], v[190:193], v[82:85]
	v_mfma_f32_16x16x32_bf16 v[74:77], v[166:169], v[190:193], v[74:77]
	v_mfma_f32_16x16x32_bf16 v[66:69], v[166:169], v[206:209], v[66:69]
	v_mfma_f32_16x16x32_bf16 v[70:73], v[158:161], v[206:209], v[70:73]
	s_barrier
	s_setprio 0
	s_mov_b32 m0, s70
	v_lshl_add_u64 v[134:135], s[38:39], 0, v[132:133]
	ds_read_b128 v[170:173], v137 offset:16384
	ds_read_b128 v[174:177], v137 offset:17408
	ds_read_b128 v[178:181], v137 offset:18432
	ds_read_b128 v[182:185], v137 offset:19456
	ds_read_b128 v[186:189], v137 offset:20480
	ds_read_b128 v[190:193], v137 offset:21504
	ds_read_b128 v[202:205], v137 offset:22528
	ds_read_b128 v[206:209], v137 offset:23552
	global_load_lds_dwordx4 v[134:135], off
	v_lshl_add_u64 v[210:211], s[38:39], 0, v[130:131]
	s_mov_b32 m0, s67
	v_lshl_add_u64 v[212:213], s[46:47], 0, v[132:133]
	global_load_lds_dwordx4 v[210:211], off
	s_mov_b32 m0, s69
	v_lshl_add_u64 v[214:215], s[36:37], 0, v[130:131]
	global_load_lds_dwordx4 v[212:213], off
	v_lshl_add_u64 v[212:213], s[46:47], 0, v[130:131]
	s_mov_b32 m0, s68
	s_nop 0
	global_load_lds_dwordx4 v[212:213], off
	v_lshl_add_u64 v[212:213], s[36:37], 0, v[132:133]
	s_mov_b32 m0, s53
	s_nop 0
	global_load_lds_dwordx4 v[212:213], off
	s_mov_b32 m0, s56
	s_nop 0
	global_load_lds_dwordx4 v[214:215], off
	s_waitcnt vmcnt(8)
	s_waitcnt lgkmcnt(0)
	s_setprio 1
	s_barrier
	v_mfma_f32_16x16x32_bf16 v[62:65], v[138:141], v[170:173], v[62:65]
	v_mfma_f32_16x16x32_bf16 v[58:61], v[146:149], v[170:173], v[58:61]
	v_mfma_f32_16x16x32_bf16 v[46:49], v[146:149], v[178:181], v[46:49]
	v_mfma_f32_16x16x32_bf16 v[54:57], v[138:141], v[178:181], v[54:57]
	v_mfma_f32_16x16x32_bf16 v[38:41], v[138:141], v[186:189], v[38:41]
	v_mfma_f32_16x16x32_bf16 v[30:33], v[146:149], v[186:189], v[30:33]
	v_mfma_f32_16x16x32_bf16 v[14:17], v[146:149], v[202:205], v[14:17]
	v_mfma_f32_16x16x32_bf16 v[22:25], v[138:141], v[202:205], v[22:25]
	v_mfma_f32_16x16x32_bf16 v[62:65], v[142:145], v[174:177], v[62:65]
	v_mfma_f32_16x16x32_bf16 v[58:61], v[150:153], v[174:177], v[58:61]
	v_mfma_f32_16x16x32_bf16 v[46:49], v[150:153], v[182:185], v[46:49]
	v_mfma_f32_16x16x32_bf16 v[54:57], v[142:145], v[182:185], v[54:57]
	v_mfma_f32_16x16x32_bf16 v[38:41], v[142:145], v[190:193], v[38:41]
	v_mfma_f32_16x16x32_bf16 v[30:33], v[150:153], v[190:193], v[30:33]
	v_mfma_f32_16x16x32_bf16 v[14:17], v[150:153], v[206:209], v[14:17]
	v_mfma_f32_16x16x32_bf16 v[22:25], v[142:145], v[206:209], v[22:25]
	v_mfma_f32_16x16x32_bf16 v[50:53], v[154:157], v[170:173], v[50:53]
	v_mfma_f32_16x16x32_bf16 v[42:45], v[162:165], v[170:173], v[42:45]
	v_mfma_f32_16x16x32_bf16 v[26:29], v[162:165], v[178:181], v[26:29]
	v_mfma_f32_16x16x32_bf16 v[34:37], v[154:157], v[178:181], v[34:37]
	v_mfma_f32_16x16x32_bf16 v[18:21], v[154:157], v[186:189], v[18:21]
	v_mfma_f32_16x16x32_bf16 v[10:13], v[162:165], v[186:189], v[10:13]
	v_mfma_f32_16x16x32_bf16 v[2:5], v[162:165], v[202:205], v[2:5]
	v_mfma_f32_16x16x32_bf16 v[6:9], v[154:157], v[202:205], v[6:9]
	v_mfma_f32_16x16x32_bf16 v[50:53], v[158:161], v[174:177], v[50:53]
	v_mfma_f32_16x16x32_bf16 v[42:45], v[166:169], v[174:177], v[42:45]
	v_mfma_f32_16x16x32_bf16 v[26:29], v[166:169], v[182:185], v[26:29]
	v_mfma_f32_16x16x32_bf16 v[34:37], v[158:161], v[182:185], v[34:37]
	v_mfma_f32_16x16x32_bf16 v[18:21], v[158:161], v[190:193], v[18:21]
	v_mfma_f32_16x16x32_bf16 v[10:13], v[166:169], v[190:193], v[10:13]
	v_mfma_f32_16x16x32_bf16 v[2:5], v[166:169], v[206:209], v[2:5]
	v_mfma_f32_16x16x32_bf16 v[6:9], v[158:161], v[206:209], v[6:9]
	s_barrier
	s_setprio 0
	v_add_u32_e32 v150, s66, v136
	v_add_u32_e32 v166, s65, v136
	ds_read_b128 v[138:141], v150
	ds_read_b128 v[142:145], v150 offset:1024
	ds_read_b128 v[146:149], v150 offset:2048
	ds_read_b128 v[150:153], v150 offset:3072
	ds_read_b128 v[154:157], v166
	ds_read_b128 v[158:161], v166 offset:1024
	ds_read_b128 v[162:165], v166 offset:2048
	ds_read_b128 v[166:169], v166 offset:3072
	s_mov_b32 m0, s57
	v_lshl_add_u64 v[216:217], s[30:31], 0, v[132:133]
	ds_read_b128 v[170:173], v137 offset:32768
	ds_read_b128 v[174:177], v137 offset:33792
	ds_read_b128 v[178:181], v137 offset:34816
	ds_read_b128 v[182:185], v137 offset:35840
	ds_read_b128 v[186:189], v137 offset:36864
	ds_read_b128 v[190:193], v137 offset:37888
	ds_read_b128 v[202:205], v137 offset:38912
	ds_read_b128 v[206:209], v137 offset:39936
	global_load_lds_dwordx4 v[216:217], off
	v_lshl_add_u64 v[216:217], s[30:31], 0, v[130:131]
	s_mov_b32 m0, s58
	s_nop 0
	global_load_lds_dwordx4 v[216:217], off
	s_waitcnt vmcnt(8)
	s_waitcnt lgkmcnt(0)
	s_setprio 1
	s_barrier
	v_mfma_f32_16x16x32_bf16 v[126:129], v[138:141], v[170:173], v[126:129]
	v_mfma_f32_16x16x32_bf16 v[122:125], v[146:149], v[170:173], v[122:125]
	v_mfma_f32_16x16x32_bf16 v[110:113], v[146:149], v[178:181], v[110:113]
	v_mfma_f32_16x16x32_bf16 v[118:121], v[138:141], v[178:181], v[118:121]
	v_mfma_f32_16x16x32_bf16 v[102:105], v[138:141], v[186:189], v[102:105]
	v_mfma_f32_16x16x32_bf16 v[94:97], v[146:149], v[186:189], v[94:97]
	v_mfma_f32_16x16x32_bf16 v[78:81], v[146:149], v[202:205], v[78:81]
	v_mfma_f32_16x16x32_bf16 v[86:89], v[138:141], v[202:205], v[86:89]
	v_mfma_f32_16x16x32_bf16 v[126:129], v[142:145], v[174:177], v[126:129]
	v_mfma_f32_16x16x32_bf16 v[122:125], v[150:153], v[174:177], v[122:125]
	v_mfma_f32_16x16x32_bf16 v[110:113], v[150:153], v[182:185], v[110:113]
	v_mfma_f32_16x16x32_bf16 v[118:121], v[142:145], v[182:185], v[118:121]
	v_mfma_f32_16x16x32_bf16 v[102:105], v[142:145], v[190:193], v[102:105]
	v_mfma_f32_16x16x32_bf16 v[94:97], v[150:153], v[190:193], v[94:97]
	v_mfma_f32_16x16x32_bf16 v[78:81], v[150:153], v[206:209], v[78:81]
	v_mfma_f32_16x16x32_bf16 v[86:89], v[142:145], v[206:209], v[86:89]
	v_mfma_f32_16x16x32_bf16 v[114:117], v[154:157], v[170:173], v[114:117]
	v_mfma_f32_16x16x32_bf16 v[106:109], v[162:165], v[170:173], v[106:109]
	v_mfma_f32_16x16x32_bf16 v[90:93], v[162:165], v[178:181], v[90:93]
	v_mfma_f32_16x16x32_bf16 v[98:101], v[154:157], v[178:181], v[98:101]
	v_mfma_f32_16x16x32_bf16 v[82:85], v[154:157], v[186:189], v[82:85]
	v_mfma_f32_16x16x32_bf16 v[74:77], v[162:165], v[186:189], v[74:77]
	v_mfma_f32_16x16x32_bf16 v[66:69], v[162:165], v[202:205], v[66:69]
	v_mfma_f32_16x16x32_bf16 v[70:73], v[154:157], v[202:205], v[70:73]
	v_mfma_f32_16x16x32_bf16 v[114:117], v[158:161], v[174:177], v[114:117]
	v_mfma_f32_16x16x32_bf16 v[106:109], v[166:169], v[174:177], v[106:109]
	v_mfma_f32_16x16x32_bf16 v[90:93], v[166:169], v[182:185], v[90:93]
	v_mfma_f32_16x16x32_bf16 v[98:101], v[158:161], v[182:185], v[98:101]
	v_mfma_f32_16x16x32_bf16 v[82:85], v[158:161], v[190:193], v[82:85]
	v_mfma_f32_16x16x32_bf16 v[74:77], v[166:169], v[190:193], v[74:77]
	v_mfma_f32_16x16x32_bf16 v[66:69], v[166:169], v[206:209], v[66:69]
	v_mfma_f32_16x16x32_bf16 v[70:73], v[158:161], v[206:209], v[70:73]
	s_barrier
	s_setprio 0
	s_mov_b32 m0, s64
	v_lshl_add_u64 v[134:135], v[134:135], 0, s[10:11]
	ds_read_b128 v[170:173], v137 offset:49152
	ds_read_b128 v[174:177], v137 offset:50176
	ds_read_b128 v[178:181], v137 offset:51200
	ds_read_b128 v[182:185], v137 offset:52224
	ds_read_b128 v[186:189], v137 offset:53248
	ds_read_b128 v[190:193], v137 offset:54272
	ds_read_b128 v[202:205], v137 offset:55296
	ds_read_b128 v[206:209], v137 offset:56320
	global_load_lds_dwordx4 v[134:135], off
	v_lshl_add_u64 v[134:135], v[210:211], 0, s[10:11]
	s_mov_b32 m0, s21
	s_nop 0
	global_load_lds_dwordx4 v[134:135], off
	v_lshl_add_u64 v[134:135], s[28:29], 0, v[132:133]
	s_mov_b32 m0, s72
	s_nop 0
	global_load_lds_dwordx4 v[134:135], off
	v_lshl_add_u64 v[134:135], s[28:29], 0, v[130:131]
	s_mov_b32 m0, s71
	s_nop 0
	global_load_lds_dwordx4 v[134:135], off
	v_lshl_add_u64 v[134:135], v[212:213], 0, s[10:11]
	s_mov_b32 m0, s59
	s_nop 0
	global_load_lds_dwordx4 v[134:135], off
	v_lshl_add_u64 v[134:135], v[214:215], 0, s[10:11]
	s_mov_b32 m0, s60
	s_nop 0
	global_load_lds_dwordx4 v[134:135], off
	s_waitcnt vmcnt(8)
	s_waitcnt lgkmcnt(0)
	s_setprio 1
	s_barrier
	v_mfma_f32_16x16x32_bf16 v[62:65], v[138:141], v[170:173], v[62:65]
	v_mfma_f32_16x16x32_bf16 v[58:61], v[146:149], v[170:173], v[58:61]
	v_mfma_f32_16x16x32_bf16 v[46:49], v[146:149], v[178:181], v[46:49]
	v_mfma_f32_16x16x32_bf16 v[54:57], v[138:141], v[178:181], v[54:57]
	v_mfma_f32_16x16x32_bf16 v[38:41], v[138:141], v[186:189], v[38:41]
	v_mfma_f32_16x16x32_bf16 v[30:33], v[146:149], v[186:189], v[30:33]
	v_mfma_f32_16x16x32_bf16 v[14:17], v[146:149], v[202:205], v[14:17]
	v_mfma_f32_16x16x32_bf16 v[22:25], v[138:141], v[202:205], v[22:25]
	v_mfma_f32_16x16x32_bf16 v[62:65], v[142:145], v[174:177], v[62:65]
	v_mfma_f32_16x16x32_bf16 v[58:61], v[150:153], v[174:177], v[58:61]
	v_mfma_f32_16x16x32_bf16 v[46:49], v[150:153], v[182:185], v[46:49]
	v_mfma_f32_16x16x32_bf16 v[54:57], v[142:145], v[182:185], v[54:57]
	v_mfma_f32_16x16x32_bf16 v[38:41], v[142:145], v[190:193], v[38:41]
	v_mfma_f32_16x16x32_bf16 v[30:33], v[150:153], v[190:193], v[30:33]
	v_mfma_f32_16x16x32_bf16 v[14:17], v[150:153], v[206:209], v[14:17]
	v_mfma_f32_16x16x32_bf16 v[22:25], v[142:145], v[206:209], v[22:25]
	v_mfma_f32_16x16x32_bf16 v[50:53], v[154:157], v[170:173], v[50:53]
	v_mfma_f32_16x16x32_bf16 v[42:45], v[162:165], v[170:173], v[42:45]
	v_mfma_f32_16x16x32_bf16 v[26:29], v[162:165], v[178:181], v[26:29]
	v_mfma_f32_16x16x32_bf16 v[34:37], v[154:157], v[178:181], v[34:37]
	v_mfma_f32_16x16x32_bf16 v[18:21], v[154:157], v[186:189], v[18:21]
	v_mfma_f32_16x16x32_bf16 v[10:13], v[162:165], v[186:189], v[10:13]
	v_mfma_f32_16x16x32_bf16 v[2:5], v[162:165], v[202:205], v[2:5]
	v_mfma_f32_16x16x32_bf16 v[6:9], v[154:157], v[202:205], v[6:9]
	v_mfma_f32_16x16x32_bf16 v[50:53], v[158:161], v[174:177], v[50:53]
	v_mfma_f32_16x16x32_bf16 v[42:45], v[166:169], v[174:177], v[42:45]
	v_mfma_f32_16x16x32_bf16 v[26:29], v[166:169], v[182:185], v[26:29]
	v_mfma_f32_16x16x32_bf16 v[34:37], v[158:161], v[182:185], v[34:37]
	v_mfma_f32_16x16x32_bf16 v[18:21], v[158:161], v[190:193], v[18:21]
	v_mfma_f32_16x16x32_bf16 v[10:13], v[166:169], v[190:193], v[10:13]
	v_mfma_f32_16x16x32_bf16 v[2:5], v[166:169], v[206:209], v[2:5]
	v_mfma_f32_16x16x32_bf16 v[6:9], v[158:161], v[206:209], v[6:9]
	s_barrier
	s_setprio 0
	s_andn2_b64 vcc, exec, s[26:27]
	s_mov_b64 s[28:29], -1
	s_mov_b64 s[26:27], 0
	s_movk_i32 s21, 0x100
	s_cbranch_vccz .LBB0_1002
	s_and_b64 vcc, exec, s[16:17]
	s_cbranch_vccz .LBB0_1005
	s_barrier

.LBB0_1087:
	s_add_u32 s30, s28, 0xfff80080
	s_addc_u32 s31, s29, -1
	s_cmp_eq_u32 s83, 28
	s_cselect_b32 s43, s23, s31
	s_cselect_b32 s42, s44, s30
	s_cselect_b32 s31, s21, s82
	s_cselect_b32 s30, s45, s81
	s_add_i32 s84, 0, 0x10000
	s_add_i32 s86, 0, 0x14000
	v_add_u32_e32 v62, s84, v229
	v_add_u32_e32 v158, s86, v229
	ds_read_b128 v[42:45], v62
	ds_read_b128 v[46:49], v62 offset:1024
	ds_read_b128 v[58:61], v62 offset:2048
	ds_read_b128 v[62:65], v62 offset:3072
	ds_read_b128 v[146:149], v158
	ds_read_b128 v[150:153], v158 offset:1024
	ds_read_b128 v[154:157], v158 offset:2048
	ds_read_b128 v[158:161], v158 offset:3072
	v_lshl_add_u64 v[208:209], s[28:29], 0, v[204:205]
	s_add_i32 m0, s71, 0xc000
	ds_read_b128 v[162:165], v230
	ds_read_b128 v[166:169], v230 offset:1024
	ds_read_b128 v[170:173], v230 offset:2048
	ds_read_b128 v[174:177], v230 offset:3072
	ds_read_b128 v[178:181], v230 offset:4096
	ds_read_b128 v[182:185], v230 offset:5120
	ds_read_b128 v[186:189], v230 offset:6144
	ds_read_b128 v[190:193], v230 offset:7168
	global_load_lds_dwordx4 v[208:209], off
	v_lshl_add_u64 v[208:209], s[28:29], 0, v[206:207]
	s_add_i32 m0, s71, 0xe000
	s_nop 0
	global_load_lds_dwordx4 v[208:209], off
	s_waitcnt vmcnt(8)
	s_waitcnt lgkmcnt(0)
	s_setprio 1
	s_barrier
	v_mfma_f32_16x16x32_bf16 v[142:145], v[42:45], v[162:165], v[142:145]
	v_mfma_f32_16x16x32_bf16 v[138:141], v[58:61], v[162:165], v[138:141]
	v_mfma_f32_16x16x32_bf16 v[122:125], v[58:61], v[170:173], v[122:125]
	v_mfma_f32_16x16x32_bf16 v[126:129], v[42:45], v[170:173], v[126:129]
	v_mfma_f32_16x16x32_bf16 v[110:113], v[42:45], v[178:181], v[110:113]
	v_mfma_f32_16x16x32_bf16 v[106:109], v[58:61], v[178:181], v[106:109]
	v_mfma_f32_16x16x32_bf16 v[90:93], v[58:61], v[186:189], v[90:93]
	v_mfma_f32_16x16x32_bf16 v[94:97], v[42:45], v[186:189], v[94:97]
	v_mfma_f32_16x16x32_bf16 v[142:145], v[46:49], v[166:169], v[142:145]
	v_mfma_f32_16x16x32_bf16 v[138:141], v[62:65], v[166:169], v[138:141]
	v_mfma_f32_16x16x32_bf16 v[122:125], v[62:65], v[174:177], v[122:125]
	v_mfma_f32_16x16x32_bf16 v[126:129], v[46:49], v[174:177], v[126:129]
	v_mfma_f32_16x16x32_bf16 v[110:113], v[46:49], v[182:185], v[110:113]
	v_mfma_f32_16x16x32_bf16 v[106:109], v[62:65], v[182:185], v[106:109]
	v_mfma_f32_16x16x32_bf16 v[90:93], v[62:65], v[190:193], v[90:93]
	v_mfma_f32_16x16x32_bf16 v[94:97], v[46:49], v[190:193], v[94:97]
	v_mfma_f32_16x16x32_bf16 v[134:137], v[146:149], v[162:165], v[134:137]
	v_mfma_f32_16x16x32_bf16 v[130:133], v[154:157], v[162:165], v[130:133]
	v_mfma_f32_16x16x32_bf16 v[114:117], v[154:157], v[170:173], v[114:117]
	v_mfma_f32_16x16x32_bf16 v[118:121], v[146:149], v[170:173], v[118:121]
	v_mfma_f32_16x16x32_bf16 v[102:105], v[146:149], v[178:181], v[102:105]
	v_mfma_f32_16x16x32_bf16 v[98:101], v[154:157], v[178:181], v[98:101]
	v_mfma_f32_16x16x32_bf16 v[82:85], v[154:157], v[186:189], v[82:85]
	v_mfma_f32_16x16x32_bf16 v[86:89], v[146:149], v[186:189], v[86:89]
	v_mfma_f32_16x16x32_bf16 v[134:137], v[150:153], v[166:169], v[134:137]
	v_mfma_f32_16x16x32_bf16 v[130:133], v[158:161], v[166:169], v[130:133]
	v_mfma_f32_16x16x32_bf16 v[114:117], v[158:161], v[174:177], v[114:117]
	v_mfma_f32_16x16x32_bf16 v[118:121], v[150:153], v[174:177], v[118:121]
	v_mfma_f32_16x16x32_bf16 v[102:105], v[150:153], v[182:185], v[102:105]
	v_mfma_f32_16x16x32_bf16 v[98:101], v[158:161], v[182:185], v[98:101]
	v_mfma_f32_16x16x32_bf16 v[82:85], v[158:161], v[190:193], v[82:85]
	v_mfma_f32_16x16x32_bf16 v[86:89], v[150:153], v[190:193], v[86:89]
	s_barrier
	s_setprio 0
	s_add_i32 s84, s84, s70
	v_lshl_add_u64 v[208:209], s[30:31], 0, v[194:195]
	s_mov_b32 m0, s84
	ds_read_b128 v[162:165], v230 offset:16384
	ds_read_b128 v[166:169], v230 offset:17408
	ds_read_b128 v[170:173], v230 offset:18432
	ds_read_b128 v[174:177], v230 offset:19456
	ds_read_b128 v[178:181], v230 offset:20480
	ds_read_b128 v[182:185], v230 offset:21504
	ds_read_b128 v[186:189], v230 offset:22528
	ds_read_b128 v[190:193], v230 offset:23552
	global_load_lds_dwordx4 v[208:209], off
	s_add_i32 m0, s84, 0x2000
	s_add_u32 s84, s30, 0x80000
	v_lshl_add_u64 v[210:211], s[30:31], 0, v[202:203]
	s_addc_u32 s85, s31, 0
	s_add_i32 s86, s86, s70
	global_load_lds_dwordx4 v[210:211], off
	v_lshl_add_u64 v[212:213], s[84:85], 0, v[194:195]
	s_mov_b32 m0, s86
	v_lshl_add_u64 v[214:215], s[42:43], 0, v[202:203]
	global_load_lds_dwordx4 v[212:213], off
	v_lshl_add_u64 v[212:213], s[84:85], 0, v[202:203]
	s_add_i32 m0, s86, 0x2000
	s_nop 0
	global_load_lds_dwordx4 v[212:213], off
	v_lshl_add_u64 v[212:213], s[42:43], 0, v[194:195]
	s_mov_b32 m0, s71
	s_nop 0
	global_load_lds_dwordx4 v[212:213], off
	s_mov_b32 m0, s72
	s_nop 0
	global_load_lds_dwordx4 v[214:215], off
	s_waitcnt vmcnt(8)
	s_waitcnt lgkmcnt(0)
	s_setprio 1
	s_barrier
	v_mfma_f32_16x16x32_bf16 v[78:81], v[42:45], v[162:165], v[78:81]
	v_mfma_f32_16x16x32_bf16 v[74:77], v[58:61], v[162:165], v[74:77]
	v_mfma_f32_16x16x32_bf16 v[50:53], v[58:61], v[170:173], v[50:53]
	v_mfma_f32_16x16x32_bf16 v[54:57], v[42:45], v[170:173], v[54:57]
	v_mfma_f32_16x16x32_bf16 v[30:33], v[42:45], v[178:181], v[30:33]
	v_mfma_f32_16x16x32_bf16 v[26:29], v[58:61], v[178:181], v[26:29]
	v_mfma_f32_16x16x32_bf16 v[10:13], v[58:61], v[186:189], v[10:13]
	v_mfma_f32_16x16x32_bf16 v[14:17], v[42:45], v[186:189], v[14:17]
	v_mfma_f32_16x16x32_bf16 v[78:81], v[46:49], v[166:169], v[78:81]
	v_mfma_f32_16x16x32_bf16 v[74:77], v[62:65], v[166:169], v[74:77]
	v_mfma_f32_16x16x32_bf16 v[50:53], v[62:65], v[174:177], v[50:53]
	v_mfma_f32_16x16x32_bf16 v[54:57], v[46:49], v[174:177], v[54:57]
	v_mfma_f32_16x16x32_bf16 v[30:33], v[46:49], v[182:185], v[30:33]
	v_mfma_f32_16x16x32_bf16 v[26:29], v[62:65], v[182:185], v[26:29]
	v_mfma_f32_16x16x32_bf16 v[10:13], v[62:65], v[190:193], v[10:13]
	v_mfma_f32_16x16x32_bf16 v[14:17], v[46:49], v[190:193], v[14:17]
	v_mfma_f32_16x16x32_bf16 v[38:41], v[146:149], v[170:173], v[38:41]
	v_mfma_f32_16x16x32_bf16 v[34:37], v[154:157], v[170:173], v[34:37]
	v_mfma_f32_16x16x32_bf16 v[22:25], v[146:149], v[178:181], v[22:25]
	v_mfma_f32_16x16x32_bf16 v[18:21], v[154:157], v[178:181], v[18:21]
	v_mfma_f32_16x16x32_bf16 v[6:9], v[146:149], v[186:189], v[6:9]
	v_mfma_f32_16x16x32_bf16 v[2:5], v[154:157], v[186:189], v[2:5]
	v_mfma_f32_16x16x32_bf16 v[42:45], v[146:149], v[162:165], v[70:73]
	v_mfma_f32_16x16x32_bf16 v[46:49], v[154:157], v[162:165], v[66:69]
	v_mfma_f32_16x16x32_bf16 v[38:41], v[150:153], v[174:177], v[38:41]
	v_mfma_f32_16x16x32_bf16 v[34:37], v[158:161], v[174:177], v[34:37]
	v_mfma_f32_16x16x32_bf16 v[22:25], v[150:153], v[182:185], v[22:25]
	v_mfma_f32_16x16x32_bf16 v[18:21], v[158:161], v[182:185], v[18:21]
	v_mfma_f32_16x16x32_bf16 v[6:9], v[150:153], v[190:193], v[6:9]
	v_mfma_f32_16x16x32_bf16 v[2:5], v[158:161], v[190:193], v[2:5]
	v_mfma_f32_16x16x32_bf16 v[42:45], v[150:153], v[166:169], v[42:45]
	v_mfma_f32_16x16x32_bf16 v[46:49], v[158:161], v[166:169], v[46:49]
	s_barrier
	s_setprio 0
	s_add_i32 s84, 0, 0x18000
	s_add_i32 s85, 0, 0x1c000
	v_add_u32_e32 v70, s84, v229
	v_add_u32_e32 v158, s85, v229
	ds_read_b128 v[58:61], v70
	ds_read_b128 v[62:65], v70 offset:1024
	ds_read_b128 v[66:69], v70 offset:2048
	ds_read_b128 v[70:73], v70 offset:3072
	ds_read_b128 v[146:149], v158
	ds_read_b128 v[150:153], v158 offset:1024
	ds_read_b128 v[154:157], v158 offset:2048
	ds_read_b128 v[158:161], v158 offset:3072
	s_add_u32 s42, s42, 0x80000
	s_addc_u32 s43, s43, 0
	s_mov_b32 m0, s73
	v_lshl_add_u64 v[216:217], s[42:43], 0, v[194:195]
	ds_read_b128 v[162:165], v230 offset:32768
	ds_read_b128 v[166:169], v230 offset:33792
	ds_read_b128 v[170:173], v230 offset:34816
	ds_read_b128 v[174:177], v230 offset:35840
	ds_read_b128 v[178:181], v230 offset:36864
	ds_read_b128 v[182:185], v230 offset:37888
	ds_read_b128 v[186:189], v230 offset:38912
	ds_read_b128 v[190:193], v230 offset:39936
	global_load_lds_dwordx4 v[216:217], off
	v_lshl_add_u64 v[216:217], s[42:43], 0, v[202:203]
	s_mov_b32 m0, s74
	s_nop 0
	global_load_lds_dwordx4 v[216:217], off
	s_waitcnt vmcnt(8)
	s_waitcnt lgkmcnt(0)
	s_setprio 1
	s_barrier
	v_mfma_f32_16x16x32_bf16 v[142:145], v[58:61], v[162:165], v[142:145]
	v_mfma_f32_16x16x32_bf16 v[138:141], v[66:69], v[162:165], v[138:141]
	v_mfma_f32_16x16x32_bf16 v[122:125], v[66:69], v[170:173], v[122:125]
	v_mfma_f32_16x16x32_bf16 v[126:129], v[58:61], v[170:173], v[126:129]
	v_mfma_f32_16x16x32_bf16 v[110:113], v[58:61], v[178:181], v[110:113]
	v_mfma_f32_16x16x32_bf16 v[106:109], v[66:69], v[178:181], v[106:109]
	v_mfma_f32_16x16x32_bf16 v[90:93], v[66:69], v[186:189], v[90:93]
	v_mfma_f32_16x16x32_bf16 v[94:97], v[58:61], v[186:189], v[94:97]
	v_mfma_f32_16x16x32_bf16 v[142:145], v[62:65], v[166:169], v[142:145]
	v_mfma_f32_16x16x32_bf16 v[138:141], v[70:73], v[166:169], v[138:141]
	v_mfma_f32_16x16x32_bf16 v[122:125], v[70:73], v[174:177], v[122:125]
	v_mfma_f32_16x16x32_bf16 v[126:129], v[62:65], v[174:177], v[126:129]
	v_mfma_f32_16x16x32_bf16 v[110:113], v[62:65], v[182:185], v[110:113]
	v_mfma_f32_16x16x32_bf16 v[106:109], v[70:73], v[182:185], v[106:109]
	v_mfma_f32_16x16x32_bf16 v[90:93], v[70:73], v[190:193], v[90:93]
	v_mfma_f32_16x16x32_bf16 v[94:97], v[62:65], v[190:193], v[94:97]
	v_mfma_f32_16x16x32_bf16 v[134:137], v[146:149], v[162:165], v[134:137]
	v_mfma_f32_16x16x32_bf16 v[130:133], v[154:157], v[162:165], v[130:133]
	v_mfma_f32_16x16x32_bf16 v[114:117], v[154:157], v[170:173], v[114:117]
	v_mfma_f32_16x16x32_bf16 v[118:121], v[146:149], v[170:173], v[118:121]
	v_mfma_f32_16x16x32_bf16 v[102:105], v[146:149], v[178:181], v[102:105]
	v_mfma_f32_16x16x32_bf16 v[98:101], v[154:157], v[178:181], v[98:101]
	v_mfma_f32_16x16x32_bf16 v[82:85], v[154:157], v[186:189], v[82:85]
	v_mfma_f32_16x16x32_bf16 v[86:89], v[146:149], v[186:189], v[86:89]
	v_mfma_f32_16x16x32_bf16 v[134:137], v[150:153], v[166:169], v[134:137]
	v_mfma_f32_16x16x32_bf16 v[130:133], v[158:161], v[166:169], v[130:133]
	v_mfma_f32_16x16x32_bf16 v[114:117], v[158:161], v[174:177], v[114:117]
	v_mfma_f32_16x16x32_bf16 v[118:121], v[150:153], v[174:177], v[118:121]
	v_mfma_f32_16x16x32_bf16 v[102:105], v[150:153], v[182:185], v[102:105]
	v_mfma_f32_16x16x32_bf16 v[98:101], v[158:161], v[182:185], v[98:101]
	v_mfma_f32_16x16x32_bf16 v[82:85], v[158:161], v[190:193], v[82:85]
	v_mfma_f32_16x16x32_bf16 v[86:89], v[150:153], v[190:193], v[86:89]
	s_barrier
	s_setprio 0
	s_add_i32 s42, s84, s70
	v_lshl_add_u64 v[208:209], v[208:209], 0, s[10:11]
	s_mov_b32 m0, s42
	ds_read_b128 v[162:165], v230 offset:49152
	ds_read_b128 v[166:169], v230 offset:50176
	ds_read_b128 v[170:173], v230 offset:51200
	ds_read_b128 v[174:177], v230 offset:52224
	ds_read_b128 v[178:181], v230 offset:53248
	ds_read_b128 v[182:185], v230 offset:54272
	ds_read_b128 v[186:189], v230 offset:55296
	ds_read_b128 v[190:193], v230 offset:56320
	global_load_lds_dwordx4 v[208:209], off
	s_add_i32 m0, s42, 0x2000
	s_add_u32 s30, s30, 0x80080
	v_lshl_add_u64 v[208:209], v[210:211], 0, s[10:11]
	s_addc_u32 s31, s31, 0
	s_add_i32 s42, s85, s70
	global_load_lds_dwordx4 v[208:209], off
	v_lshl_add_u64 v[208:209], s[30:31], 0, v[194:195]
	s_mov_b32 m0, s42
	s_nop 0
	global_load_lds_dwordx4 v[208:209], off
	v_lshl_add_u64 v[208:209], s[30:31], 0, v[202:203]
	s_add_i32 m0, s42, 0x2000
	s_nop 0
	global_load_lds_dwordx4 v[208:209], off
	v_lshl_add_u64 v[208:209], v[212:213], 0, s[10:11]
	s_mov_b32 m0, s79
	s_nop 0
	global_load_lds_dwordx4 v[208:209], off
	v_lshl_add_u64 v[208:209], v[214:215], 0, s[10:11]
	s_mov_b32 m0, s80
	s_nop 0
	global_load_lds_dwordx4 v[208:209], off
	s_waitcnt vmcnt(8)
	s_waitcnt lgkmcnt(0)
	s_setprio 1
	s_barrier
	v_mfma_f32_16x16x32_bf16 v[78:81], v[58:61], v[162:165], v[78:81]
	v_mfma_f32_16x16x32_bf16 v[74:77], v[66:69], v[162:165], v[74:77]
	v_mfma_f32_16x16x32_bf16 v[50:53], v[66:69], v[170:173], v[50:53]
	v_mfma_f32_16x16x32_bf16 v[54:57], v[58:61], v[170:173], v[54:57]
	v_mfma_f32_16x16x32_bf16 v[30:33], v[58:61], v[178:181], v[30:33]
	v_mfma_f32_16x16x32_bf16 v[26:29], v[66:69], v[178:181], v[26:29]
	v_mfma_f32_16x16x32_bf16 v[10:13], v[66:69], v[186:189], v[10:13]
	v_mfma_f32_16x16x32_bf16 v[14:17], v[58:61], v[186:189], v[14:17]
	v_mfma_f32_16x16x32_bf16 v[78:81], v[62:65], v[166:169], v[78:81]
	v_mfma_f32_16x16x32_bf16 v[74:77], v[70:73], v[166:169], v[74:77]
	v_mfma_f32_16x16x32_bf16 v[50:53], v[70:73], v[174:177], v[50:53]
	v_mfma_f32_16x16x32_bf16 v[54:57], v[62:65], v[174:177], v[54:57]
	v_mfma_f32_16x16x32_bf16 v[30:33], v[62:65], v[182:185], v[30:33]
	v_mfma_f32_16x16x32_bf16 v[26:29], v[70:73], v[182:185], v[26:29]
	v_mfma_f32_16x16x32_bf16 v[10:13], v[70:73], v[190:193], v[10:13]
	v_mfma_f32_16x16x32_bf16 v[14:17], v[62:65], v[190:193], v[14:17]
	v_mfma_f32_16x16x32_bf16 v[42:45], v[146:149], v[162:165], v[42:45]
	v_mfma_f32_16x16x32_bf16 v[70:73], v[150:153], v[166:169], v[42:45]
	v_mfma_f32_16x16x32_bf16 v[42:45], v[154:157], v[162:165], v[46:49]
	v_mfma_f32_16x16x32_bf16 v[38:41], v[146:149], v[170:173], v[38:41]
	v_mfma_f32_16x16x32_bf16 v[34:37], v[154:157], v[170:173], v[34:37]
	v_mfma_f32_16x16x32_bf16 v[22:25], v[146:149], v[178:181], v[22:25]
	v_mfma_f32_16x16x32_bf16 v[18:21], v[154:157], v[178:181], v[18:21]
	v_mfma_f32_16x16x32_bf16 v[6:9], v[146:149], v[186:189], v[6:9]
	v_mfma_f32_16x16x32_bf16 v[2:5], v[154:157], v[186:189], v[2:5]
	v_mfma_f32_16x16x32_bf16 v[66:69], v[158:161], v[166:169], v[42:45]
	v_mfma_f32_16x16x32_bf16 v[38:41], v[150:153], v[174:177], v[38:41]
	v_mfma_f32_16x16x32_bf16 v[34:37], v[158:161], v[174:177], v[34:37]
	v_mfma_f32_16x16x32_bf16 v[22:25], v[150:153], v[182:185], v[22:25]
	v_mfma_f32_16x16x32_bf16 v[18:21], v[158:161], v[182:185], v[18:21]
	v_mfma_f32_16x16x32_bf16 v[6:9], v[150:153], v[190:193], v[6:9]
	v_mfma_f32_16x16x32_bf16 v[2:5], v[158:161], v[190:193], v[2:5]
	s_barrier
	s_setprio 0
	s_add_i32 s83, s83, 2
	s_add_u32 s28, s28, 0x100
	s_addc_u32 s29, s29, 0
	s_add_u32 s81, s81, 0x100
	s_addc_u32 s82, s82, 0
	s_cmp_gt_u32 s83, 29
	s_cbranch_scc0 .LBB0_1087
	s_and_b64 vcc, exec, s[16:17]
	s_cbranch_vccz .LBB0_1090
	s_barrier

.LBB0_1272:
	s_add_u32 s30, s28, 0xfff80080
	s_addc_u32 s31, s29, -1
	s_add_i32 s66, 0, 0x10000
	s_cmp_eq_u32 s65, 28
	s_cselect_b32 s37, s60, s31
	s_cselect_b32 s36, s61, s30
	s_cselect_b32 s31, s21, s64
	s_cselect_b32 s30, s62, s63
	s_add_i32 s68, 0, 0x14000
	v_add_u32_e32 v126, s66, v156
	v_add_u32_e32 v154, s68, v156
	ds_read_b128 v[114:117], v126
	ds_read_b128 v[118:121], v126 offset:1024
	ds_read_b128 v[122:125], v126 offset:2048
	ds_read_b128 v[126:129], v126 offset:3072
	ds_read_b128 v[158:161], v154
	ds_read_b128 v[162:165], v154 offset:1024
	ds_read_b128 v[166:169], v154 offset:2048
	ds_read_b128 v[170:173], v154 offset:3072
	v_lshl_add_u64 v[154:155], s[28:29], 0, v[150:151]
	s_add_i32 m0, s49, 0xc000
	ds_read_b128 v[174:177], v157
	ds_read_b128 v[178:181], v157 offset:1024
	ds_read_b128 v[182:185], v157 offset:2048
	ds_read_b128 v[186:189], v157 offset:3072
	ds_read_b128 v[190:193], v157 offset:4096
	ds_read_b128 v[202:205], v157 offset:5120
	ds_read_b128 v[206:209], v157 offset:6144
	ds_read_b128 v[210:213], v157 offset:7168
	global_load_lds_dwordx4 v[154:155], off
	v_lshl_add_u64 v[154:155], s[28:29], 0, v[152:153]
	s_add_i32 m0, s49, 0xe000
	s_nop 0
	global_load_lds_dwordx4 v[154:155], off
	s_waitcnt vmcnt(8)
	s_waitcnt lgkmcnt(0)
	s_setprio 1
	s_barrier
	v_mfma_f32_16x16x32_bf16 v[142:145], v[114:117], v[174:177], v[142:145]
	v_mfma_f32_16x16x32_bf16 v[138:141], v[122:125], v[174:177], v[138:141]
	v_mfma_f32_16x16x32_bf16 v[106:109], v[122:125], v[182:185], v[106:109]
	v_mfma_f32_16x16x32_bf16 v[110:113], v[114:117], v[182:185], v[110:113]
	v_mfma_f32_16x16x32_bf16 v[94:97], v[114:117], v[190:193], v[94:97]
	v_mfma_f32_16x16x32_bf16 v[90:93], v[122:125], v[190:193], v[90:93]
	v_mfma_f32_16x16x32_bf16 v[74:77], v[122:125], v[206:209], v[74:77]
	v_mfma_f32_16x16x32_bf16 v[78:81], v[114:117], v[206:209], v[78:81]
	v_mfma_f32_16x16x32_bf16 v[142:145], v[118:121], v[178:181], v[142:145]
	v_mfma_f32_16x16x32_bf16 v[138:141], v[126:129], v[178:181], v[138:141]
	v_mfma_f32_16x16x32_bf16 v[106:109], v[126:129], v[186:189], v[106:109]
	v_mfma_f32_16x16x32_bf16 v[110:113], v[118:121], v[186:189], v[110:113]
	v_mfma_f32_16x16x32_bf16 v[94:97], v[118:121], v[202:205], v[94:97]
	v_mfma_f32_16x16x32_bf16 v[90:93], v[126:129], v[202:205], v[90:93]
	v_mfma_f32_16x16x32_bf16 v[74:77], v[126:129], v[210:213], v[74:77]
	v_mfma_f32_16x16x32_bf16 v[78:81], v[118:121], v[210:213], v[78:81]
	v_mfma_f32_16x16x32_bf16 v[134:137], v[158:161], v[174:177], v[134:137]
	v_mfma_f32_16x16x32_bf16 v[130:133], v[166:169], v[174:177], v[130:133]
	v_mfma_f32_16x16x32_bf16 v[98:101], v[166:169], v[182:185], v[98:101]
	v_mfma_f32_16x16x32_bf16 v[102:105], v[158:161], v[182:185], v[102:105]
	v_mfma_f32_16x16x32_bf16 v[86:89], v[158:161], v[190:193], v[86:89]
	v_mfma_f32_16x16x32_bf16 v[82:85], v[166:169], v[190:193], v[82:85]
	v_mfma_f32_16x16x32_bf16 v[66:69], v[166:169], v[206:209], v[66:69]
	v_mfma_f32_16x16x32_bf16 v[70:73], v[158:161], v[206:209], v[70:73]
	v_mfma_f32_16x16x32_bf16 v[134:137], v[162:165], v[178:181], v[134:137]
	v_mfma_f32_16x16x32_bf16 v[130:133], v[170:173], v[178:181], v[130:133]
	v_mfma_f32_16x16x32_bf16 v[98:101], v[170:173], v[186:189], v[98:101]
	v_mfma_f32_16x16x32_bf16 v[102:105], v[162:165], v[186:189], v[102:105]
	v_mfma_f32_16x16x32_bf16 v[86:89], v[162:165], v[202:205], v[86:89]
	v_mfma_f32_16x16x32_bf16 v[82:85], v[170:173], v[202:205], v[82:85]
	v_mfma_f32_16x16x32_bf16 v[66:69], v[170:173], v[210:213], v[66:69]
	v_mfma_f32_16x16x32_bf16 v[70:73], v[162:165], v[210:213], v[70:73]
	s_barrier
	s_setprio 0
	s_add_i32 s66, s66, s48
	v_lshl_add_u64 v[154:155], s[30:31], 0, v[146:147]
	s_mov_b32 m0, s66
	ds_read_b128 v[174:177], v157 offset:16384
	ds_read_b128 v[178:181], v157 offset:17408
	ds_read_b128 v[182:185], v157 offset:18432
	ds_read_b128 v[186:189], v157 offset:19456
	ds_read_b128 v[190:193], v157 offset:20480
	ds_read_b128 v[202:205], v157 offset:21504
	ds_read_b128 v[206:209], v157 offset:22528
	ds_read_b128 v[210:213], v157 offset:23552
	global_load_lds_dwordx4 v[154:155], off
	s_add_i32 m0, s66, 0x2000
	s_add_u32 s66, s30, 0x80000
	v_lshl_add_u64 v[214:215], s[30:31], 0, v[148:149]
	s_addc_u32 s67, s31, 0
	s_add_i32 s68, s68, s48
	global_load_lds_dwordx4 v[214:215], off
	v_lshl_add_u64 v[216:217], s[66:67], 0, v[146:147]
	s_mov_b32 m0, s68
	v_lshl_add_u64 v[228:229], s[36:37], 0, v[148:149]
	global_load_lds_dwordx4 v[216:217], off
	v_lshl_add_u64 v[216:217], s[66:67], 0, v[148:149]
	s_add_i32 m0, s68, 0x2000
	s_nop 0
	global_load_lds_dwordx4 v[216:217], off
	v_lshl_add_u64 v[216:217], s[36:37], 0, v[146:147]
	s_mov_b32 m0, s49
	s_nop 0
	global_load_lds_dwordx4 v[216:217], off
	s_mov_b32 m0, s50
	s_nop 0
	global_load_lds_dwordx4 v[228:229], off
	s_waitcnt vmcnt(8)
	s_waitcnt lgkmcnt(0)
	s_setprio 1
	s_barrier
	v_mfma_f32_16x16x32_bf16 v[62:65], v[114:117], v[174:177], v[62:65]
	v_mfma_f32_16x16x32_bf16 v[58:61], v[122:125], v[174:177], v[58:61]
	v_mfma_f32_16x16x32_bf16 v[42:45], v[122:125], v[182:185], v[42:45]
	v_mfma_f32_16x16x32_bf16 v[46:49], v[114:117], v[182:185], v[46:49]
	v_mfma_f32_16x16x32_bf16 v[30:33], v[114:117], v[190:193], v[30:33]
	v_mfma_f32_16x16x32_bf16 v[26:29], v[122:125], v[190:193], v[26:29]
	v_mfma_f32_16x16x32_bf16 v[10:13], v[122:125], v[206:209], v[10:13]
	v_mfma_f32_16x16x32_bf16 v[14:17], v[114:117], v[206:209], v[14:17]
	v_mfma_f32_16x16x32_bf16 v[62:65], v[118:121], v[178:181], v[62:65]
	v_mfma_f32_16x16x32_bf16 v[58:61], v[126:129], v[178:181], v[58:61]
	v_mfma_f32_16x16x32_bf16 v[42:45], v[126:129], v[186:189], v[42:45]
	v_mfma_f32_16x16x32_bf16 v[46:49], v[118:121], v[186:189], v[46:49]
	v_mfma_f32_16x16x32_bf16 v[30:33], v[118:121], v[202:205], v[30:33]
	v_mfma_f32_16x16x32_bf16 v[26:29], v[126:129], v[202:205], v[26:29]
	v_mfma_f32_16x16x32_bf16 v[10:13], v[126:129], v[210:213], v[10:13]
	v_mfma_f32_16x16x32_bf16 v[14:17], v[118:121], v[210:213], v[14:17]
	v_mfma_f32_16x16x32_bf16 v[54:57], v[158:161], v[174:177], v[54:57]
	v_mfma_f32_16x16x32_bf16 v[50:53], v[166:169], v[174:177], v[50:53]
	v_mfma_f32_16x16x32_bf16 v[34:37], v[166:169], v[182:185], v[34:37]
	v_mfma_f32_16x16x32_bf16 v[38:41], v[158:161], v[182:185], v[38:41]
	v_mfma_f32_16x16x32_bf16 v[22:25], v[158:161], v[190:193], v[22:25]
	v_mfma_f32_16x16x32_bf16 v[18:21], v[166:169], v[190:193], v[18:21]
	v_mfma_f32_16x16x32_bf16 v[2:5], v[166:169], v[206:209], v[2:5]
	v_mfma_f32_16x16x32_bf16 v[6:9], v[158:161], v[206:209], v[6:9]
	v_mfma_f32_16x16x32_bf16 v[54:57], v[162:165], v[178:181], v[54:57]
	v_mfma_f32_16x16x32_bf16 v[50:53], v[170:173], v[178:181], v[50:53]
	v_mfma_f32_16x16x32_bf16 v[34:37], v[170:173], v[186:189], v[34:37]
	v_mfma_f32_16x16x32_bf16 v[38:41], v[162:165], v[186:189], v[38:41]
	v_mfma_f32_16x16x32_bf16 v[22:25], v[162:165], v[202:205], v[22:25]
	v_mfma_f32_16x16x32_bf16 v[18:21], v[170:173], v[202:205], v[18:21]
	v_mfma_f32_16x16x32_bf16 v[2:5], v[170:173], v[210:213], v[2:5]
	v_mfma_f32_16x16x32_bf16 v[6:9], v[162:165], v[210:213], v[6:9]
	s_barrier
	s_setprio 0
	s_add_i32 s66, 0, 0x18000
	s_add_i32 s67, 0, 0x1c000
	v_add_u32_e32 v126, s66, v156
	v_add_u32_e32 v170, s67, v156
	ds_read_b128 v[114:117], v126
	ds_read_b128 v[118:121], v126 offset:1024
	ds_read_b128 v[122:125], v126 offset:2048
	ds_read_b128 v[126:129], v126 offset:3072
	ds_read_b128 v[158:161], v170
	ds_read_b128 v[162:165], v170 offset:1024
	ds_read_b128 v[166:169], v170 offset:2048
	ds_read_b128 v[170:173], v170 offset:3072
	s_add_u32 s36, s36, 0x80000
	s_addc_u32 s37, s37, 0
	s_mov_b32 m0, s51
	v_lshl_add_u64 v[230:231], s[36:37], 0, v[146:147]
	ds_read_b128 v[174:177], v157 offset:32768
	ds_read_b128 v[178:181], v157 offset:33792
	ds_read_b128 v[182:185], v157 offset:34816
	ds_read_b128 v[186:189], v157 offset:35840
	ds_read_b128 v[190:193], v157 offset:36864
	ds_read_b128 v[202:205], v157 offset:37888
	ds_read_b128 v[206:209], v157 offset:38912
	ds_read_b128 v[210:213], v157 offset:39936
	global_load_lds_dwordx4 v[230:231], off
	v_lshl_add_u64 v[230:231], s[36:37], 0, v[148:149]
	s_mov_b32 m0, s52
	s_nop 0
	global_load_lds_dwordx4 v[230:231], off
	s_waitcnt vmcnt(8)
	s_waitcnt lgkmcnt(0)
	s_setprio 1
	s_barrier
	v_mfma_f32_16x16x32_bf16 v[142:145], v[114:117], v[174:177], v[142:145]
	v_mfma_f32_16x16x32_bf16 v[138:141], v[122:125], v[174:177], v[138:141]
	v_mfma_f32_16x16x32_bf16 v[106:109], v[122:125], v[182:185], v[106:109]
	v_mfma_f32_16x16x32_bf16 v[110:113], v[114:117], v[182:185], v[110:113]
	v_mfma_f32_16x16x32_bf16 v[94:97], v[114:117], v[190:193], v[94:97]
	v_mfma_f32_16x16x32_bf16 v[90:93], v[122:125], v[190:193], v[90:93]
	v_mfma_f32_16x16x32_bf16 v[74:77], v[122:125], v[206:209], v[74:77]
	v_mfma_f32_16x16x32_bf16 v[78:81], v[114:117], v[206:209], v[78:81]
	v_mfma_f32_16x16x32_bf16 v[142:145], v[118:121], v[178:181], v[142:145]
	v_mfma_f32_16x16x32_bf16 v[138:141], v[126:129], v[178:181], v[138:141]
	v_mfma_f32_16x16x32_bf16 v[106:109], v[126:129], v[186:189], v[106:109]
	v_mfma_f32_16x16x32_bf16 v[110:113], v[118:121], v[186:189], v[110:113]
	v_mfma_f32_16x16x32_bf16 v[94:97], v[118:121], v[202:205], v[94:97]
	v_mfma_f32_16x16x32_bf16 v[90:93], v[126:129], v[202:205], v[90:93]
	v_mfma_f32_16x16x32_bf16 v[74:77], v[126:129], v[210:213], v[74:77]
	v_mfma_f32_16x16x32_bf16 v[78:81], v[118:121], v[210:213], v[78:81]
	v_mfma_f32_16x16x32_bf16 v[134:137], v[158:161], v[174:177], v[134:137]
	v_mfma_f32_16x16x32_bf16 v[130:133], v[166:169], v[174:177], v[130:133]
	v_mfma_f32_16x16x32_bf16 v[98:101], v[166:169], v[182:185], v[98:101]
	v_mfma_f32_16x16x32_bf16 v[102:105], v[158:161], v[182:185], v[102:105]
	v_mfma_f32_16x16x32_bf16 v[86:89], v[158:161], v[190:193], v[86:89]
	v_mfma_f32_16x16x32_bf16 v[82:85], v[166:169], v[190:193], v[82:85]
	v_mfma_f32_16x16x32_bf16 v[66:69], v[166:169], v[206:209], v[66:69]
	v_mfma_f32_16x16x32_bf16 v[70:73], v[158:161], v[206:209], v[70:73]
	v_mfma_f32_16x16x32_bf16 v[134:137], v[162:165], v[178:181], v[134:137]
	v_mfma_f32_16x16x32_bf16 v[130:133], v[170:173], v[178:181], v[130:133]
	v_mfma_f32_16x16x32_bf16 v[98:101], v[170:173], v[186:189], v[98:101]
	v_mfma_f32_16x16x32_bf16 v[102:105], v[162:165], v[186:189], v[102:105]
	v_mfma_f32_16x16x32_bf16 v[86:89], v[162:165], v[202:205], v[86:89]
	v_mfma_f32_16x16x32_bf16 v[82:85], v[170:173], v[202:205], v[82:85]
	v_mfma_f32_16x16x32_bf16 v[66:69], v[170:173], v[210:213], v[66:69]
	v_mfma_f32_16x16x32_bf16 v[70:73], v[162:165], v[210:213], v[70:73]
	s_barrier
	s_setprio 0
	s_add_i32 s36, s66, s48
	v_lshl_add_u64 v[154:155], v[154:155], 0, s[10:11]
	s_mov_b32 m0, s36
	ds_read_b128 v[174:177], v157 offset:49152
	ds_read_b128 v[178:181], v157 offset:50176
	ds_read_b128 v[182:185], v157 offset:51200
	ds_read_b128 v[186:189], v157 offset:52224
	ds_read_b128 v[190:193], v157 offset:53248
	ds_read_b128 v[202:205], v157 offset:54272
	ds_read_b128 v[206:209], v157 offset:55296
	ds_read_b128 v[210:213], v157 offset:56320
	global_load_lds_dwordx4 v[154:155], off
	s_add_i32 m0, s36, 0x2000
	s_add_u32 s30, s30, 0x80080
	v_lshl_add_u64 v[154:155], v[214:215], 0, s[10:11]
	s_addc_u32 s31, s31, 0
	s_add_i32 s36, s67, s48
	global_load_lds_dwordx4 v[154:155], off
	v_lshl_add_u64 v[154:155], s[30:31], 0, v[146:147]
	s_mov_b32 m0, s36
	s_nop 0
	global_load_lds_dwordx4 v[154:155], off
	v_lshl_add_u64 v[154:155], s[30:31], 0, v[148:149]
	s_add_i32 m0, s36, 0x2000
	s_nop 0
	global_load_lds_dwordx4 v[154:155], off
	v_lshl_add_u64 v[154:155], v[216:217], 0, s[10:11]
	s_mov_b32 m0, s53
	s_nop 0
	global_load_lds_dwordx4 v[154:155], off
	v_lshl_add_u64 v[154:155], v[228:229], 0, s[10:11]
	s_mov_b32 m0, s56
	s_nop 0
	global_load_lds_dwordx4 v[154:155], off
	s_waitcnt vmcnt(8)
	s_waitcnt lgkmcnt(0)
	s_setprio 1
	s_barrier
	v_mfma_f32_16x16x32_bf16 v[62:65], v[114:117], v[174:177], v[62:65]
	v_mfma_f32_16x16x32_bf16 v[58:61], v[122:125], v[174:177], v[58:61]
	v_mfma_f32_16x16x32_bf16 v[42:45], v[122:125], v[182:185], v[42:45]
	v_mfma_f32_16x16x32_bf16 v[46:49], v[114:117], v[182:185], v[46:49]
	v_mfma_f32_16x16x32_bf16 v[30:33], v[114:117], v[190:193], v[30:33]
	v_mfma_f32_16x16x32_bf16 v[26:29], v[122:125], v[190:193], v[26:29]
	v_mfma_f32_16x16x32_bf16 v[10:13], v[122:125], v[206:209], v[10:13]
	v_mfma_f32_16x16x32_bf16 v[14:17], v[114:117], v[206:209], v[14:17]
	v_mfma_f32_16x16x32_bf16 v[62:65], v[118:121], v[178:181], v[62:65]
	v_mfma_f32_16x16x32_bf16 v[58:61], v[126:129], v[178:181], v[58:61]
	v_mfma_f32_16x16x32_bf16 v[42:45], v[126:129], v[186:189], v[42:45]
	v_mfma_f32_16x16x32_bf16 v[46:49], v[118:121], v[186:189], v[46:49]
	v_mfma_f32_16x16x32_bf16 v[30:33], v[118:121], v[202:205], v[30:33]
	v_mfma_f32_16x16x32_bf16 v[26:29], v[126:129], v[202:205], v[26:29]
	v_mfma_f32_16x16x32_bf16 v[10:13], v[126:129], v[210:213], v[10:13]
	v_mfma_f32_16x16x32_bf16 v[14:17], v[118:121], v[210:213], v[14:17]
	v_mfma_f32_16x16x32_bf16 v[54:57], v[158:161], v[174:177], v[54:57]
	v_mfma_f32_16x16x32_bf16 v[50:53], v[166:169], v[174:177], v[50:53]
	v_mfma_f32_16x16x32_bf16 v[34:37], v[166:169], v[182:185], v[34:37]
	v_mfma_f32_16x16x32_bf16 v[38:41], v[158:161], v[182:185], v[38:41]
	v_mfma_f32_16x16x32_bf16 v[22:25], v[158:161], v[190:193], v[22:25]
	v_mfma_f32_16x16x32_bf16 v[18:21], v[166:169], v[190:193], v[18:21]
	v_mfma_f32_16x16x32_bf16 v[2:5], v[166:169], v[206:209], v[2:5]
	v_mfma_f32_16x16x32_bf16 v[6:9], v[158:161], v[206:209], v[6:9]
	v_mfma_f32_16x16x32_bf16 v[54:57], v[162:165], v[178:181], v[54:57]
	v_mfma_f32_16x16x32_bf16 v[50:53], v[170:173], v[178:181], v[50:53]
	v_mfma_f32_16x16x32_bf16 v[34:37], v[170:173], v[186:189], v[34:37]
	v_mfma_f32_16x16x32_bf16 v[38:41], v[162:165], v[186:189], v[38:41]
	v_mfma_f32_16x16x32_bf16 v[22:25], v[162:165], v[202:205], v[22:25]
	v_mfma_f32_16x16x32_bf16 v[18:21], v[170:173], v[202:205], v[18:21]
	v_mfma_f32_16x16x32_bf16 v[2:5], v[170:173], v[210:213], v[2:5]
	v_mfma_f32_16x16x32_bf16 v[6:9], v[162:165], v[210:213], v[6:9]
	s_barrier
	s_setprio 0
	s_add_i32 s65, s65, 2
	s_add_u32 s28, s28, 0x100
	s_addc_u32 s29, s29, 0
	s_add_u32 s63, s63, 0x100
	s_addc_u32 s64, s64, 0
	s_cmp_gt_u32 s65, 29
	s_cbranch_scc0 .LBB0_1272
	s_and_b64 vcc, exec, s[18:19]
	s_cbranch_vccz .LBB0_1275
	s_barrier

.LBB0_1346:
	s_or_b32 s20, s30, 1
	s_mul_hi_u32 s31, s20, 0x280000
	s_mul_i32 s42, s20, 0x280000
	s_add_u32 s20, s56, s18
	s_addc_u32 s21, s57, s19
	s_add_u32 s18, s16, 0x280000
	s_addc_u32 s19, s17, 0
	s_add_i32 s44, 0, 0x10000
	s_add_i32 s45, 0, 0x14000
	v_add_u32_e32 v146, s44, v44
	v_add_u32_e32 v162, s45, v44
	ds_read_b128 v[46:49], v146
	ds_read_b128 v[58:61], v146 offset:1024
	ds_read_b128 v[62:65], v146 offset:2048
	ds_read_b128 v[146:149], v146 offset:3072
	ds_read_b128 v[150:153], v162
	ds_read_b128 v[154:157], v162 offset:1024
	ds_read_b128 v[158:161], v162 offset:2048
	ds_read_b128 v[162:165], v162 offset:3072
	s_add_u32 s42, s62, s42
	s_addc_u32 s43, s63, s31
	v_lshl_add_u64 v[206:207], s[42:43], 0, v[194:195]
	s_add_i32 m0, s24, 0xc000
	ds_read_b128 v[166:169], v45
	ds_read_b128 v[170:173], v45 offset:1024
	ds_read_b128 v[174:177], v45 offset:2048
	ds_read_b128 v[178:181], v45 offset:3072
	ds_read_b128 v[182:185], v45 offset:4096
	ds_read_b128 v[186:189], v45 offset:5120
	ds_read_b128 v[190:193], v45 offset:6144
	ds_read_b128 v[202:205], v45 offset:7168
	global_load_lds_dwordx4 v[206:207], off
	v_lshl_add_u64 v[206:207], s[42:43], 0, v[42:43]
	s_add_i32 m0, s24, 0xe000
	s_nop 0
	global_load_lds_dwordx4 v[206:207], off
	s_waitcnt vmcnt(8)
	s_waitcnt lgkmcnt(0)
	s_setprio 1
	s_barrier
	v_mfma_f32_16x16x32_bf16 v[142:145], v[46:49], v[166:169], v[142:145]
	v_mfma_f32_16x16x32_bf16 v[138:141], v[62:65], v[166:169], v[138:141]
	v_mfma_f32_16x16x32_bf16 v[122:125], v[62:65], v[174:177], v[122:125]
	v_mfma_f32_16x16x32_bf16 v[126:129], v[46:49], v[174:177], v[126:129]
	v_mfma_f32_16x16x32_bf16 v[110:113], v[46:49], v[182:185], v[110:113]
	v_mfma_f32_16x16x32_bf16 v[106:109], v[62:65], v[182:185], v[106:109]
	v_mfma_f32_16x16x32_bf16 v[90:93], v[62:65], v[190:193], v[90:93]
	v_mfma_f32_16x16x32_bf16 v[94:97], v[46:49], v[190:193], v[94:97]
	v_mfma_f32_16x16x32_bf16 v[142:145], v[58:61], v[170:173], v[142:145]
	v_mfma_f32_16x16x32_bf16 v[138:141], v[146:149], v[170:173], v[138:141]
	v_mfma_f32_16x16x32_bf16 v[122:125], v[146:149], v[178:181], v[122:125]
	v_mfma_f32_16x16x32_bf16 v[126:129], v[58:61], v[178:181], v[126:129]
	v_mfma_f32_16x16x32_bf16 v[110:113], v[58:61], v[186:189], v[110:113]
	v_mfma_f32_16x16x32_bf16 v[106:109], v[146:149], v[186:189], v[106:109]
	v_mfma_f32_16x16x32_bf16 v[90:93], v[146:149], v[202:205], v[90:93]
	v_mfma_f32_16x16x32_bf16 v[94:97], v[58:61], v[202:205], v[94:97]
	v_mfma_f32_16x16x32_bf16 v[134:137], v[150:153], v[166:169], v[134:137]
	v_mfma_f32_16x16x32_bf16 v[130:133], v[158:161], v[166:169], v[130:133]
	v_mfma_f32_16x16x32_bf16 v[114:117], v[158:161], v[174:177], v[114:117]
	v_mfma_f32_16x16x32_bf16 v[118:121], v[150:153], v[174:177], v[118:121]
	v_mfma_f32_16x16x32_bf16 v[102:105], v[150:153], v[182:185], v[102:105]
	v_mfma_f32_16x16x32_bf16 v[98:101], v[158:161], v[182:185], v[98:101]
	v_mfma_f32_16x16x32_bf16 v[82:85], v[158:161], v[190:193], v[82:85]
	v_mfma_f32_16x16x32_bf16 v[86:89], v[150:153], v[190:193], v[86:89]
	v_mfma_f32_16x16x32_bf16 v[134:137], v[154:157], v[170:173], v[134:137]
	v_mfma_f32_16x16x32_bf16 v[130:133], v[162:165], v[170:173], v[130:133]
	v_mfma_f32_16x16x32_bf16 v[114:117], v[162:165], v[178:181], v[114:117]
	v_mfma_f32_16x16x32_bf16 v[118:121], v[154:157], v[178:181], v[118:121]
	v_mfma_f32_16x16x32_bf16 v[102:105], v[154:157], v[186:189], v[102:105]
	v_mfma_f32_16x16x32_bf16 v[98:101], v[162:165], v[186:189], v[98:101]
	v_mfma_f32_16x16x32_bf16 v[82:85], v[162:165], v[202:205], v[82:85]
	v_mfma_f32_16x16x32_bf16 v[86:89], v[154:157], v[202:205], v[86:89]
	s_barrier
	s_setprio 0
	s_add_i32 s31, s44, s23
	v_lshl_add_u64 v[206:207], s[20:21], 0, v[194:195]
	s_mov_b32 m0, s31
	ds_read_b128 v[166:169], v45 offset:16384
	ds_read_b128 v[170:173], v45 offset:17408
	ds_read_b128 v[174:177], v45 offset:18432
	ds_read_b128 v[178:181], v45 offset:19456
	ds_read_b128 v[182:185], v45 offset:20480
	ds_read_b128 v[186:189], v45 offset:21504
	ds_read_b128 v[190:193], v45 offset:22528
	ds_read_b128 v[202:205], v45 offset:23552
	global_load_lds_dwordx4 v[206:207], off
	s_add_i32 m0, s31, 0x2000
	s_add_u32 s42, s20, 0x4000
	v_lshl_add_u64 v[206:207], s[20:21], 0, v[42:43]
	s_addc_u32 s43, s21, 0
	s_add_i32 s31, s45, s23
	global_load_lds_dwordx4 v[206:207], off
	v_lshl_add_u64 v[206:207], s[42:43], 0, v[194:195]
	s_mov_b32 m0, s31
	s_nop 0
	global_load_lds_dwordx4 v[206:207], off
	v_lshl_add_u64 v[206:207], s[42:43], 0, v[42:43]
	s_add_i32 m0, s31, 0x2000
	s_nop 0
	global_load_lds_dwordx4 v[206:207], off
	v_lshl_add_u64 v[206:207], s[16:17], 0, v[194:195]
	s_mov_b32 m0, s24
	s_nop 0
	global_load_lds_dwordx4 v[206:207], off
	v_lshl_add_u64 v[206:207], s[16:17], 0, v[42:43]
	s_mov_b32 m0, s25
	s_nop 0
	global_load_lds_dwordx4 v[206:207], off
	s_waitcnt vmcnt(8)
	s_waitcnt lgkmcnt(0)
	s_setprio 1
	s_barrier
	v_mfma_f32_16x16x32_bf16 v[78:81], v[46:49], v[166:169], v[78:81]
	v_mfma_f32_16x16x32_bf16 v[74:77], v[62:65], v[166:169], v[74:77]
	v_mfma_f32_16x16x32_bf16 v[50:53], v[62:65], v[174:177], v[50:53]
	v_mfma_f32_16x16x32_bf16 v[54:57], v[46:49], v[174:177], v[54:57]
	v_mfma_f32_16x16x32_bf16 v[30:33], v[46:49], v[182:185], v[30:33]
	v_mfma_f32_16x16x32_bf16 v[26:29], v[62:65], v[182:185], v[26:29]
	v_mfma_f32_16x16x32_bf16 v[10:13], v[62:65], v[190:193], v[10:13]
	v_mfma_f32_16x16x32_bf16 v[14:17], v[46:49], v[190:193], v[14:17]
	v_mfma_f32_16x16x32_bf16 v[78:81], v[58:61], v[170:173], v[78:81]
	v_mfma_f32_16x16x32_bf16 v[74:77], v[146:149], v[170:173], v[74:77]
	v_mfma_f32_16x16x32_bf16 v[50:53], v[146:149], v[178:181], v[50:53]
	v_mfma_f32_16x16x32_bf16 v[54:57], v[58:61], v[178:181], v[54:57]
	v_mfma_f32_16x16x32_bf16 v[30:33], v[58:61], v[186:189], v[30:33]
	v_mfma_f32_16x16x32_bf16 v[26:29], v[146:149], v[186:189], v[26:29]
	v_mfma_f32_16x16x32_bf16 v[10:13], v[146:149], v[202:205], v[10:13]
	v_mfma_f32_16x16x32_bf16 v[14:17], v[58:61], v[202:205], v[14:17]
	v_mfma_f32_16x16x32_bf16 v[38:41], v[150:153], v[174:177], v[38:41]
	v_mfma_f32_16x16x32_bf16 v[34:37], v[158:161], v[174:177], v[34:37]
	v_mfma_f32_16x16x32_bf16 v[22:25], v[150:153], v[182:185], v[22:25]
	v_mfma_f32_16x16x32_bf16 v[18:21], v[158:161], v[182:185], v[18:21]
	v_mfma_f32_16x16x32_bf16 v[6:9], v[150:153], v[190:193], v[6:9]
	v_mfma_f32_16x16x32_bf16 v[2:5], v[158:161], v[190:193], v[2:5]
	v_mfma_f32_16x16x32_bf16 v[46:49], v[150:153], v[166:169], v[70:73]
	v_mfma_f32_16x16x32_bf16 v[58:61], v[158:161], v[166:169], v[66:69]
	v_mfma_f32_16x16x32_bf16 v[38:41], v[154:157], v[178:181], v[38:41]
	v_mfma_f32_16x16x32_bf16 v[34:37], v[162:165], v[178:181], v[34:37]
	v_mfma_f32_16x16x32_bf16 v[22:25], v[154:157], v[186:189], v[22:25]
	v_mfma_f32_16x16x32_bf16 v[18:21], v[162:165], v[186:189], v[18:21]
	v_mfma_f32_16x16x32_bf16 v[6:9], v[154:157], v[202:205], v[6:9]
	v_mfma_f32_16x16x32_bf16 v[2:5], v[162:165], v[202:205], v[2:5]
	v_mfma_f32_16x16x32_bf16 v[46:49], v[154:157], v[170:173], v[46:49]
	v_mfma_f32_16x16x32_bf16 v[58:61], v[162:165], v[170:173], v[58:61]
	s_barrier
	s_setprio 0
	s_add_i32 s31, 0, 0x18000
	s_add_i32 s42, 0, 0x1c000
	v_add_u32_e32 v146, s31, v44
	v_add_u32_e32 v162, s42, v44
	ds_read_b128 v[62:65], v146
	ds_read_b128 v[66:69], v146 offset:1024
	ds_read_b128 v[70:73], v146 offset:2048
	ds_read_b128 v[146:149], v146 offset:3072
	ds_read_b128 v[150:153], v162
	ds_read_b128 v[154:157], v162 offset:1024
	ds_read_b128 v[158:161], v162 offset:2048
	ds_read_b128 v[162:165], v162 offset:3072
	s_add_u32 s16, s16, 0x4000
	s_addc_u32 s17, s17, 0
	s_mov_b32 m0, s26
	v_lshl_add_u64 v[206:207], s[16:17], 0, v[194:195]
	ds_read_b128 v[166:169], v45 offset:32768
	ds_read_b128 v[170:173], v45 offset:33792
	ds_read_b128 v[174:177], v45 offset:34816
	ds_read_b128 v[178:181], v45 offset:35840
	ds_read_b128 v[182:185], v45 offset:36864
	ds_read_b128 v[186:189], v45 offset:37888
	ds_read_b128 v[190:193], v45 offset:38912
	ds_read_b128 v[202:205], v45 offset:39936
	global_load_lds_dwordx4 v[206:207], off
	v_lshl_add_u64 v[206:207], s[16:17], 0, v[42:43]
	s_mov_b32 m0, s27
	s_nop 0
	global_load_lds_dwordx4 v[206:207], off
	s_waitcnt vmcnt(8)
	s_waitcnt lgkmcnt(0)
	s_setprio 1
	s_barrier
	v_mfma_f32_16x16x32_bf16 v[142:145], v[62:65], v[166:169], v[142:145]
	v_mfma_f32_16x16x32_bf16 v[138:141], v[70:73], v[166:169], v[138:141]
	v_mfma_f32_16x16x32_bf16 v[122:125], v[70:73], v[174:177], v[122:125]
	v_mfma_f32_16x16x32_bf16 v[126:129], v[62:65], v[174:177], v[126:129]
	v_mfma_f32_16x16x32_bf16 v[110:113], v[62:65], v[182:185], v[110:113]
	v_mfma_f32_16x16x32_bf16 v[106:109], v[70:73], v[182:185], v[106:109]
	v_mfma_f32_16x16x32_bf16 v[90:93], v[70:73], v[190:193], v[90:93]
	v_mfma_f32_16x16x32_bf16 v[94:97], v[62:65], v[190:193], v[94:97]
	v_mfma_f32_16x16x32_bf16 v[142:145], v[66:69], v[170:173], v[142:145]
	v_mfma_f32_16x16x32_bf16 v[138:141], v[146:149], v[170:173], v[138:141]
	v_mfma_f32_16x16x32_bf16 v[122:125], v[146:149], v[178:181], v[122:125]
	v_mfma_f32_16x16x32_bf16 v[126:129], v[66:69], v[178:181], v[126:129]
	v_mfma_f32_16x16x32_bf16 v[110:113], v[66:69], v[186:189], v[110:113]
	v_mfma_f32_16x16x32_bf16 v[106:109], v[146:149], v[186:189], v[106:109]
	v_mfma_f32_16x16x32_bf16 v[90:93], v[146:149], v[202:205], v[90:93]
	v_mfma_f32_16x16x32_bf16 v[94:97], v[66:69], v[202:205], v[94:97]
	v_mfma_f32_16x16x32_bf16 v[134:137], v[150:153], v[166:169], v[134:137]
	v_mfma_f32_16x16x32_bf16 v[130:133], v[158:161], v[166:169], v[130:133]
	v_mfma_f32_16x16x32_bf16 v[114:117], v[158:161], v[174:177], v[114:117]
	v_mfma_f32_16x16x32_bf16 v[118:121], v[150:153], v[174:177], v[118:121]
	v_mfma_f32_16x16x32_bf16 v[102:105], v[150:153], v[182:185], v[102:105]
	v_mfma_f32_16x16x32_bf16 v[98:101], v[158:161], v[182:185], v[98:101]
	v_mfma_f32_16x16x32_bf16 v[82:85], v[158:161], v[190:193], v[82:85]
	v_mfma_f32_16x16x32_bf16 v[86:89], v[150:153], v[190:193], v[86:89]
	v_mfma_f32_16x16x32_bf16 v[134:137], v[154:157], v[170:173], v[134:137]
	v_mfma_f32_16x16x32_bf16 v[130:133], v[162:165], v[170:173], v[130:133]
	v_mfma_f32_16x16x32_bf16 v[114:117], v[162:165], v[178:181], v[114:117]
	v_mfma_f32_16x16x32_bf16 v[118:121], v[154:157], v[178:181], v[118:121]
	v_mfma_f32_16x16x32_bf16 v[102:105], v[154:157], v[186:189], v[102:105]
	v_mfma_f32_16x16x32_bf16 v[98:101], v[162:165], v[186:189], v[98:101]
	v_mfma_f32_16x16x32_bf16 v[82:85], v[162:165], v[202:205], v[82:85]
	v_mfma_f32_16x16x32_bf16 v[86:89], v[154:157], v[202:205], v[86:89]
	s_barrier
	s_setprio 0
	s_add_u32 s16, s20, 0x40000
	s_addc_u32 s17, s21, 0
	s_add_i32 s31, s31, s23
	v_lshl_add_u64 v[206:207], s[16:17], 0, v[194:195]
	s_mov_b32 m0, s31
	ds_read_b128 v[166:169], v45 offset:49152
	ds_read_b128 v[170:173], v45 offset:50176
	ds_read_b128 v[174:177], v45 offset:51200
	ds_read_b128 v[178:181], v45 offset:52224
	ds_read_b128 v[182:185], v45 offset:53248
	ds_read_b128 v[186:189], v45 offset:54272
	ds_read_b128 v[190:193], v45 offset:55296
	ds_read_b128 v[202:205], v45 offset:56320
	global_load_lds_dwordx4 v[206:207], off
	s_add_i32 m0, s31, 0x2000
	v_lshl_add_u64 v[206:207], s[16:17], 0, v[42:43]
	s_add_u32 s16, s20, 0x44000
	s_addc_u32 s17, s21, 0
	s_add_i32 s20, s42, s23
	global_load_lds_dwordx4 v[206:207], off
	v_lshl_add_u64 v[206:207], s[16:17], 0, v[194:195]
	s_mov_b32 m0, s20
	s_nop 0
	global_load_lds_dwordx4 v[206:207], off
	v_lshl_add_u64 v[206:207], s[16:17], 0, v[42:43]
	s_add_i32 m0, s20, 0x2000
	s_nop 0
	global_load_lds_dwordx4 v[206:207], off
	v_lshl_add_u64 v[206:207], s[18:19], 0, v[194:195]
	s_mov_b32 m0, s28
	s_nop 0
	global_load_lds_dwordx4 v[206:207], off
	v_lshl_add_u64 v[206:207], s[18:19], 0, v[42:43]
	s_mov_b32 m0, s29
	s_nop 0
	global_load_lds_dwordx4 v[206:207], off
	s_waitcnt vmcnt(8)
	s_waitcnt lgkmcnt(0)
	s_setprio 1
	s_barrier
	v_mfma_f32_16x16x32_bf16 v[78:81], v[62:65], v[166:169], v[78:81]
	v_mfma_f32_16x16x32_bf16 v[74:77], v[70:73], v[166:169], v[74:77]
	v_mfma_f32_16x16x32_bf16 v[50:53], v[70:73], v[174:177], v[50:53]
	v_mfma_f32_16x16x32_bf16 v[54:57], v[62:65], v[174:177], v[54:57]
	v_mfma_f32_16x16x32_bf16 v[30:33], v[62:65], v[182:185], v[30:33]
	v_mfma_f32_16x16x32_bf16 v[26:29], v[70:73], v[182:185], v[26:29]
	v_mfma_f32_16x16x32_bf16 v[10:13], v[70:73], v[190:193], v[10:13]
	v_mfma_f32_16x16x32_bf16 v[14:17], v[62:65], v[190:193], v[14:17]
	v_mfma_f32_16x16x32_bf16 v[78:81], v[66:69], v[170:173], v[78:81]
	v_mfma_f32_16x16x32_bf16 v[74:77], v[146:149], v[170:173], v[74:77]
	v_mfma_f32_16x16x32_bf16 v[50:53], v[146:149], v[178:181], v[50:53]
	v_mfma_f32_16x16x32_bf16 v[54:57], v[66:69], v[178:181], v[54:57]
	v_mfma_f32_16x16x32_bf16 v[30:33], v[66:69], v[186:189], v[30:33]
	v_mfma_f32_16x16x32_bf16 v[26:29], v[146:149], v[186:189], v[26:29]
	v_mfma_f32_16x16x32_bf16 v[10:13], v[146:149], v[202:205], v[10:13]
	v_mfma_f32_16x16x32_bf16 v[14:17], v[66:69], v[202:205], v[14:17]
	v_mfma_f32_16x16x32_bf16 v[46:49], v[150:153], v[166:169], v[46:49]
	v_mfma_f32_16x16x32_bf16 v[70:73], v[154:157], v[170:173], v[46:49]
	v_mfma_f32_16x16x32_bf16 v[46:49], v[158:161], v[166:169], v[58:61]
	v_mfma_f32_16x16x32_bf16 v[38:41], v[150:153], v[174:177], v[38:41]
	v_mfma_f32_16x16x32_bf16 v[34:37], v[158:161], v[174:177], v[34:37]
	v_mfma_f32_16x16x32_bf16 v[22:25], v[150:153], v[182:185], v[22:25]
	v_mfma_f32_16x16x32_bf16 v[18:21], v[158:161], v[182:185], v[18:21]
	v_mfma_f32_16x16x32_bf16 v[6:9], v[150:153], v[190:193], v[6:9]
	v_mfma_f32_16x16x32_bf16 v[2:5], v[158:161], v[190:193], v[2:5]
	v_mfma_f32_16x16x32_bf16 v[66:69], v[162:165], v[170:173], v[46:49]
	v_mfma_f32_16x16x32_bf16 v[38:41], v[154:157], v[178:181], v[38:41]
	v_mfma_f32_16x16x32_bf16 v[34:37], v[162:165], v[178:181], v[34:37]
	v_mfma_f32_16x16x32_bf16 v[22:25], v[154:157], v[186:189], v[22:25]
	v_mfma_f32_16x16x32_bf16 v[18:21], v[162:165], v[186:189], v[18:21]
	v_mfma_f32_16x16x32_bf16 v[6:9], v[154:157], v[202:205], v[6:9]
	v_mfma_f32_16x16x32_bf16 v[2:5], v[162:165], v[202:205], v[2:5]
	s_barrier
	s_setprio 0
	s_cmp_gt_u32 s30, 61
	s_mov_b32 s30, s4
	s_cbranch_scc1 .LBB0_1349

.LBB0_1502:
	s_or_b32 s82, s81, 1
	s_add_u32 vcc_lo, s26, vcc_lo
	s_addc_u32 vcc_hi, s27, vcc_hi
	s_and_b64 s[46:47], exec, s[46:47]
	s_cselect_b32 vcc_hi, s19, vcc_hi
	s_cselect_b32 vcc_lo, s21, vcc_lo
	s_add_u32 s46, s44, 0x280000
	s_addc_u32 s47, s45, 0
	s_add_i32 s88, 0, 0x10000
	s_add_i32 s89, 0, 0x14000
	v_add_u32_e32 v62, s88, v184
	v_add_u32_e32 v160, s89, v184
	ds_read_b128 v[50:53], v62
	ds_read_b128 v[54:57], v62 offset:1024
	ds_read_b128 v[58:61], v62 offset:2048
	ds_read_b128 v[62:65], v62 offset:3072
	ds_read_b128 v[146:149], v160
	ds_read_b128 v[150:153], v160 offset:1024
	ds_read_b128 v[156:159], v160 offset:2048
	ds_read_b128 v[160:163], v160 offset:3072
	s_mul_hi_u32 s83, s82, 0x280000
	s_mul_i32 s82, s82, 0x280000
	s_add_u32 s82, s79, s82
	s_addc_u32 s83, s80, s83
	v_lshl_add_u64 v[206:207], s[82:83], 0, v[194:195]
	s_add_i32 m0, s68, 0xc000
	ds_read_b128 v[164:167], v185
	ds_read_b128 v[168:171], v185 offset:1024
	ds_read_b128 v[172:175], v185 offset:2048
	ds_read_b128 v[176:179], v185 offset:3072
	ds_read_b128 v[180:183], v185 offset:4096
	ds_read_b128 v[186:189], v185 offset:5120
	ds_read_b128 v[190:193], v185 offset:6144
	ds_read_b128 v[202:205], v185 offset:7168
	global_load_lds_dwordx4 v[206:207], off
	v_lshl_add_u64 v[206:207], s[82:83], 0, v[154:155]
	s_add_i32 m0, s68, 0xe000
	s_nop 0
	global_load_lds_dwordx4 v[206:207], off
	s_waitcnt vmcnt(8)
	s_waitcnt lgkmcnt(0)
	s_setprio 1
	s_barrier
	v_mfma_f32_16x16x32_bf16 v[142:145], v[50:53], v[164:167], v[142:145]
	v_mfma_f32_16x16x32_bf16 v[138:141], v[58:61], v[164:167], v[138:141]
	v_mfma_f32_16x16x32_bf16 v[122:125], v[58:61], v[172:175], v[122:125]
	v_mfma_f32_16x16x32_bf16 v[126:129], v[50:53], v[172:175], v[126:129]
	v_mfma_f32_16x16x32_bf16 v[110:113], v[50:53], v[180:183], v[110:113]
	v_mfma_f32_16x16x32_bf16 v[106:109], v[58:61], v[180:183], v[106:109]
	v_mfma_f32_16x16x32_bf16 v[90:93], v[58:61], v[190:193], v[90:93]
	v_mfma_f32_16x16x32_bf16 v[94:97], v[50:53], v[190:193], v[94:97]
	v_mfma_f32_16x16x32_bf16 v[142:145], v[54:57], v[168:171], v[142:145]
	v_mfma_f32_16x16x32_bf16 v[138:141], v[62:65], v[168:171], v[138:141]
	v_mfma_f32_16x16x32_bf16 v[122:125], v[62:65], v[176:179], v[122:125]
	v_mfma_f32_16x16x32_bf16 v[126:129], v[54:57], v[176:179], v[126:129]
	v_mfma_f32_16x16x32_bf16 v[110:113], v[54:57], v[186:189], v[110:113]
	v_mfma_f32_16x16x32_bf16 v[106:109], v[62:65], v[186:189], v[106:109]
	v_mfma_f32_16x16x32_bf16 v[90:93], v[62:65], v[202:205], v[90:93]
	v_mfma_f32_16x16x32_bf16 v[94:97], v[54:57], v[202:205], v[94:97]
	v_mfma_f32_16x16x32_bf16 v[134:137], v[146:149], v[164:167], v[134:137]
	v_mfma_f32_16x16x32_bf16 v[130:133], v[156:159], v[164:167], v[130:133]
	v_mfma_f32_16x16x32_bf16 v[114:117], v[156:159], v[172:175], v[114:117]
	v_mfma_f32_16x16x32_bf16 v[118:121], v[146:149], v[172:175], v[118:121]
	v_mfma_f32_16x16x32_bf16 v[102:105], v[146:149], v[180:183], v[102:105]
	v_mfma_f32_16x16x32_bf16 v[98:101], v[156:159], v[180:183], v[98:101]
	v_mfma_f32_16x16x32_bf16 v[82:85], v[156:159], v[190:193], v[82:85]
	v_mfma_f32_16x16x32_bf16 v[86:89], v[146:149], v[190:193], v[86:89]
	v_mfma_f32_16x16x32_bf16 v[134:137], v[150:153], v[168:171], v[134:137]
	v_mfma_f32_16x16x32_bf16 v[130:133], v[160:163], v[168:171], v[130:133]
	v_mfma_f32_16x16x32_bf16 v[114:117], v[160:163], v[176:179], v[114:117]
	v_mfma_f32_16x16x32_bf16 v[118:121], v[150:153], v[176:179], v[118:121]
	v_mfma_f32_16x16x32_bf16 v[102:105], v[150:153], v[186:189], v[102:105]
	v_mfma_f32_16x16x32_bf16 v[98:101], v[160:163], v[186:189], v[98:101]
	v_mfma_f32_16x16x32_bf16 v[82:85], v[160:163], v[202:205], v[82:85]
	v_mfma_f32_16x16x32_bf16 v[86:89], v[150:153], v[202:205], v[86:89]
	s_barrier
	s_setprio 0
	s_add_i32 s82, s88, s67
	v_lshl_add_u64 v[206:207], vcc, 0, v[194:195]
	s_mov_b32 m0, s82
	ds_read_b128 v[164:167], v185 offset:16384
	ds_read_b128 v[168:171], v185 offset:17408
	ds_read_b128 v[172:175], v185 offset:18432
	ds_read_b128 v[176:179], v185 offset:19456
	ds_read_b128 v[180:183], v185 offset:20480
	ds_read_b128 v[186:189], v185 offset:21504
	ds_read_b128 v[190:193], v185 offset:22528
	ds_read_b128 v[202:205], v185 offset:23552
	global_load_lds_dwordx4 v[206:207], off
	s_add_i32 m0, s82, 0x2000
	s_add_u32 s82, vcc_lo, 0x4000
	v_lshl_add_u64 v[206:207], vcc, 0, v[154:155]
	s_addc_u32 s83, vcc_hi, 0
	s_add_i32 s88, s89, s67
	global_load_lds_dwordx4 v[206:207], off
	v_lshl_add_u64 v[206:207], s[82:83], 0, v[194:195]
	s_mov_b32 m0, s88
	s_nop 0
	global_load_lds_dwordx4 v[206:207], off
	v_lshl_add_u64 v[206:207], s[82:83], 0, v[154:155]
	s_add_i32 m0, s88, 0x2000
	s_nop 0
	global_load_lds_dwordx4 v[206:207], off
	v_lshl_add_u64 v[206:207], s[44:45], 0, v[194:195]
	s_mov_b32 m0, s68
	s_nop 0
	global_load_lds_dwordx4 v[206:207], off
	v_lshl_add_u64 v[206:207], s[44:45], 0, v[154:155]
	s_mov_b32 m0, s69
	s_nop 0
	global_load_lds_dwordx4 v[206:207], off
	s_waitcnt vmcnt(8)
	s_waitcnt lgkmcnt(0)
	s_setprio 1
	s_barrier
	v_mfma_f32_16x16x32_bf16 v[78:81], v[50:53], v[164:167], v[78:81]
	v_mfma_f32_16x16x32_bf16 v[74:77], v[58:61], v[164:167], v[74:77]
	v_mfma_f32_16x16x32_bf16 v[42:45], v[58:61], v[172:175], v[42:45]
	v_mfma_f32_16x16x32_bf16 v[46:49], v[50:53], v[172:175], v[46:49]
	v_mfma_f32_16x16x32_bf16 v[30:33], v[50:53], v[180:183], v[30:33]
	v_mfma_f32_16x16x32_bf16 v[26:29], v[58:61], v[180:183], v[26:29]
	v_mfma_f32_16x16x32_bf16 v[10:13], v[58:61], v[190:193], v[10:13]
	v_mfma_f32_16x16x32_bf16 v[14:17], v[50:53], v[190:193], v[14:17]
	v_mfma_f32_16x16x32_bf16 v[78:81], v[54:57], v[168:171], v[78:81]
	v_mfma_f32_16x16x32_bf16 v[74:77], v[62:65], v[168:171], v[74:77]
	v_mfma_f32_16x16x32_bf16 v[42:45], v[62:65], v[176:179], v[42:45]
	v_mfma_f32_16x16x32_bf16 v[46:49], v[54:57], v[176:179], v[46:49]
	v_mfma_f32_16x16x32_bf16 v[30:33], v[54:57], v[186:189], v[30:33]
	v_mfma_f32_16x16x32_bf16 v[26:29], v[62:65], v[186:189], v[26:29]
	v_mfma_f32_16x16x32_bf16 v[10:13], v[62:65], v[202:205], v[10:13]
	v_mfma_f32_16x16x32_bf16 v[14:17], v[54:57], v[202:205], v[14:17]
	v_mfma_f32_16x16x32_bf16 v[38:41], v[146:149], v[172:175], v[38:41]
	v_mfma_f32_16x16x32_bf16 v[34:37], v[156:159], v[172:175], v[34:37]
	v_mfma_f32_16x16x32_bf16 v[22:25], v[146:149], v[180:183], v[22:25]
	v_mfma_f32_16x16x32_bf16 v[18:21], v[156:159], v[180:183], v[18:21]
	v_mfma_f32_16x16x32_bf16 v[6:9], v[146:149], v[190:193], v[6:9]
	v_mfma_f32_16x16x32_bf16 v[2:5], v[156:159], v[190:193], v[2:5]
	v_mfma_f32_16x16x32_bf16 v[50:53], v[146:149], v[164:167], v[70:73]
	v_mfma_f32_16x16x32_bf16 v[54:57], v[156:159], v[164:167], v[66:69]
	v_mfma_f32_16x16x32_bf16 v[38:41], v[150:153], v[176:179], v[38:41]
	v_mfma_f32_16x16x32_bf16 v[34:37], v[160:163], v[176:179], v[34:37]
	v_mfma_f32_16x16x32_bf16 v[22:25], v[150:153], v[186:189], v[22:25]
	v_mfma_f32_16x16x32_bf16 v[18:21], v[160:163], v[186:189], v[18:21]
	v_mfma_f32_16x16x32_bf16 v[6:9], v[150:153], v[202:205], v[6:9]
	v_mfma_f32_16x16x32_bf16 v[2:5], v[160:163], v[202:205], v[2:5]
	v_mfma_f32_16x16x32_bf16 v[50:53], v[150:153], v[168:171], v[50:53]
	v_mfma_f32_16x16x32_bf16 v[54:57], v[160:163], v[168:171], v[54:57]
	s_barrier
	s_setprio 0
	s_add_i32 s82, 0, 0x18000
	s_add_i32 s83, 0, 0x1c000
	v_add_u32_e32 v70, s82, v184
	v_add_u32_e32 v160, s83, v184
	ds_read_b128 v[58:61], v70
	ds_read_b128 v[62:65], v70 offset:1024
	ds_read_b128 v[66:69], v70 offset:2048
	ds_read_b128 v[70:73], v70 offset:3072
	ds_read_b128 v[146:149], v160
	ds_read_b128 v[150:153], v160 offset:1024
	ds_read_b128 v[156:159], v160 offset:2048
	ds_read_b128 v[160:163], v160 offset:3072
	s_add_u32 s44, s44, 0x4000
	s_addc_u32 s45, s45, 0
	s_mov_b32 m0, s72
	v_lshl_add_u64 v[206:207], s[44:45], 0, v[194:195]
	ds_read_b128 v[164:167], v185 offset:32768
	ds_read_b128 v[168:171], v185 offset:33792
	ds_read_b128 v[172:175], v185 offset:34816
	ds_read_b128 v[176:179], v185 offset:35840
	ds_read_b128 v[180:183], v185 offset:36864
	ds_read_b128 v[186:189], v185 offset:37888
	ds_read_b128 v[190:193], v185 offset:38912
	ds_read_b128 v[202:205], v185 offset:39936
	global_load_lds_dwordx4 v[206:207], off
	v_lshl_add_u64 v[206:207], s[44:45], 0, v[154:155]
	s_mov_b32 m0, s73
	s_nop 0
	global_load_lds_dwordx4 v[206:207], off
	s_waitcnt vmcnt(8)
	s_waitcnt lgkmcnt(0)
	s_setprio 1
	s_barrier
	v_mfma_f32_16x16x32_bf16 v[142:145], v[58:61], v[164:167], v[142:145]
	v_mfma_f32_16x16x32_bf16 v[138:141], v[66:69], v[164:167], v[138:141]
	v_mfma_f32_16x16x32_bf16 v[122:125], v[66:69], v[172:175], v[122:125]
	v_mfma_f32_16x16x32_bf16 v[126:129], v[58:61], v[172:175], v[126:129]
	v_mfma_f32_16x16x32_bf16 v[110:113], v[58:61], v[180:183], v[110:113]
	v_mfma_f32_16x16x32_bf16 v[106:109], v[66:69], v[180:183], v[106:109]
	v_mfma_f32_16x16x32_bf16 v[90:93], v[66:69], v[190:193], v[90:93]
	v_mfma_f32_16x16x32_bf16 v[94:97], v[58:61], v[190:193], v[94:97]
	v_mfma_f32_16x16x32_bf16 v[142:145], v[62:65], v[168:171], v[142:145]
	v_mfma_f32_16x16x32_bf16 v[138:141], v[70:73], v[168:171], v[138:141]
	v_mfma_f32_16x16x32_bf16 v[122:125], v[70:73], v[176:179], v[122:125]
	v_mfma_f32_16x16x32_bf16 v[126:129], v[62:65], v[176:179], v[126:129]
	v_mfma_f32_16x16x32_bf16 v[110:113], v[62:65], v[186:189], v[110:113]
	v_mfma_f32_16x16x32_bf16 v[106:109], v[70:73], v[186:189], v[106:109]
	v_mfma_f32_16x16x32_bf16 v[90:93], v[70:73], v[202:205], v[90:93]
	v_mfma_f32_16x16x32_bf16 v[94:97], v[62:65], v[202:205], v[94:97]
	v_mfma_f32_16x16x32_bf16 v[134:137], v[146:149], v[164:167], v[134:137]
	v_mfma_f32_16x16x32_bf16 v[130:133], v[156:159], v[164:167], v[130:133]
	v_mfma_f32_16x16x32_bf16 v[114:117], v[156:159], v[172:175], v[114:117]
	v_mfma_f32_16x16x32_bf16 v[118:121], v[146:149], v[172:175], v[118:121]
	v_mfma_f32_16x16x32_bf16 v[102:105], v[146:149], v[180:183], v[102:105]
	v_mfma_f32_16x16x32_bf16 v[98:101], v[156:159], v[180:183], v[98:101]
	v_mfma_f32_16x16x32_bf16 v[82:85], v[156:159], v[190:193], v[82:85]
	v_mfma_f32_16x16x32_bf16 v[86:89], v[146:149], v[190:193], v[86:89]
	v_mfma_f32_16x16x32_bf16 v[134:137], v[150:153], v[168:171], v[134:137]
	v_mfma_f32_16x16x32_bf16 v[130:133], v[160:163], v[168:171], v[130:133]
	v_mfma_f32_16x16x32_bf16 v[114:117], v[160:163], v[176:179], v[114:117]
	v_mfma_f32_16x16x32_bf16 v[118:121], v[150:153], v[176:179], v[118:121]
	v_mfma_f32_16x16x32_bf16 v[102:105], v[150:153], v[186:189], v[102:105]
	v_mfma_f32_16x16x32_bf16 v[98:101], v[160:163], v[186:189], v[98:101]
	v_mfma_f32_16x16x32_bf16 v[82:85], v[160:163], v[202:205], v[82:85]
	v_mfma_f32_16x16x32_bf16 v[86:89], v[150:153], v[202:205], v[86:89]
	s_barrier
	s_setprio 0
	s_add_u32 s44, vcc_lo, 0x40000
	s_addc_u32 s45, vcc_hi, 0
	s_add_i32 s82, s82, s67
	v_lshl_add_u64 v[206:207], s[44:45], 0, v[194:195]
	s_mov_b32 m0, s82
	ds_read_b128 v[164:167], v185 offset:49152
	ds_read_b128 v[168:171], v185 offset:50176
	ds_read_b128 v[172:175], v185 offset:51200
	ds_read_b128 v[176:179], v185 offset:52224
	ds_read_b128 v[180:183], v185 offset:53248
	ds_read_b128 v[186:189], v185 offset:54272
	ds_read_b128 v[190:193], v185 offset:55296
	ds_read_b128 v[202:205], v185 offset:56320
	global_load_lds_dwordx4 v[206:207], off
	s_add_i32 m0, s82, 0x2000
	v_lshl_add_u64 v[206:207], s[44:45], 0, v[154:155]
	s_add_u32 s44, vcc_lo, 0x44000
	s_addc_u32 s45, vcc_hi, 0
	s_add_i32 s82, s83, s67
	global_load_lds_dwordx4 v[206:207], off
	v_lshl_add_u64 v[206:207], s[44:45], 0, v[194:195]
	s_mov_b32 m0, s82
	s_nop 0
	global_load_lds_dwordx4 v[206:207], off
	v_lshl_add_u64 v[206:207], s[44:45], 0, v[154:155]
	s_add_i32 m0, s82, 0x2000
	s_nop 0
	global_load_lds_dwordx4 v[206:207], off
	v_lshl_add_u64 v[206:207], s[46:47], 0, v[194:195]
	s_mov_b32 m0, s76
	s_nop 0
	global_load_lds_dwordx4 v[206:207], off
	v_lshl_add_u64 v[206:207], s[46:47], 0, v[154:155]
	s_mov_b32 m0, s77
	s_nop 0
	global_load_lds_dwordx4 v[206:207], off
	s_waitcnt vmcnt(8)
	s_waitcnt lgkmcnt(0)
	s_setprio 1
	s_barrier
	v_mfma_f32_16x16x32_bf16 v[78:81], v[58:61], v[164:167], v[78:81]
	v_mfma_f32_16x16x32_bf16 v[74:77], v[66:69], v[164:167], v[74:77]
	v_mfma_f32_16x16x32_bf16 v[42:45], v[66:69], v[172:175], v[42:45]
	v_mfma_f32_16x16x32_bf16 v[46:49], v[58:61], v[172:175], v[46:49]
	v_mfma_f32_16x16x32_bf16 v[30:33], v[58:61], v[180:183], v[30:33]
	v_mfma_f32_16x16x32_bf16 v[26:29], v[66:69], v[180:183], v[26:29]
	v_mfma_f32_16x16x32_bf16 v[10:13], v[66:69], v[190:193], v[10:13]
	v_mfma_f32_16x16x32_bf16 v[14:17], v[58:61], v[190:193], v[14:17]
	v_mfma_f32_16x16x32_bf16 v[78:81], v[62:65], v[168:171], v[78:81]
	v_mfma_f32_16x16x32_bf16 v[74:77], v[70:73], v[168:171], v[74:77]
	v_mfma_f32_16x16x32_bf16 v[42:45], v[70:73], v[176:179], v[42:45]
	v_mfma_f32_16x16x32_bf16 v[46:49], v[62:65], v[176:179], v[46:49]
	v_mfma_f32_16x16x32_bf16 v[30:33], v[62:65], v[186:189], v[30:33]
	v_mfma_f32_16x16x32_bf16 v[26:29], v[70:73], v[186:189], v[26:29]
	v_mfma_f32_16x16x32_bf16 v[10:13], v[70:73], v[202:205], v[10:13]
	v_mfma_f32_16x16x32_bf16 v[14:17], v[62:65], v[202:205], v[14:17]
	v_mfma_f32_16x16x32_bf16 v[50:53], v[146:149], v[164:167], v[50:53]
	v_mfma_f32_16x16x32_bf16 v[70:73], v[150:153], v[168:171], v[50:53]
	v_mfma_f32_16x16x32_bf16 v[50:53], v[156:159], v[164:167], v[54:57]
	v_mfma_f32_16x16x32_bf16 v[38:41], v[146:149], v[172:175], v[38:41]
	v_mfma_f32_16x16x32_bf16 v[34:37], v[156:159], v[172:175], v[34:37]
	v_mfma_f32_16x16x32_bf16 v[22:25], v[146:149], v[180:183], v[22:25]
	v_mfma_f32_16x16x32_bf16 v[18:21], v[156:159], v[180:183], v[18:21]
	v_mfma_f32_16x16x32_bf16 v[6:9], v[146:149], v[190:193], v[6:9]
	v_mfma_f32_16x16x32_bf16 v[2:5], v[156:159], v[190:193], v[2:5]
	v_mfma_f32_16x16x32_bf16 v[66:69], v[160:163], v[168:171], v[50:53]
	v_mfma_f32_16x16x32_bf16 v[38:41], v[150:153], v[176:179], v[38:41]
	v_mfma_f32_16x16x32_bf16 v[34:37], v[160:163], v[176:179], v[34:37]
	v_mfma_f32_16x16x32_bf16 v[22:25], v[150:153], v[186:189], v[22:25]
	v_mfma_f32_16x16x32_bf16 v[18:21], v[160:163], v[186:189], v[18:21]
	v_mfma_f32_16x16x32_bf16 v[6:9], v[150:153], v[202:205], v[6:9]
	v_mfma_f32_16x16x32_bf16 v[2:5], v[160:163], v[202:205], v[2:5]
	s_barrier
	s_setprio 0
	s_cmpk_gt_u32 s81, 0x7d
	s_mov_b32 s81, s4
	s_cbranch_scc1 .LBB0_1505
